# GEMM K-loops (FFN up/down, mix-in, up-proj, out-proj): LDS-DMA addresses as SGPR base + 32-bit lane offset (saddr form), 64-bit per-piece VALU address adds replaced by SALU
# speedup vs baseline: 1.0074x; 1.0074x over previous
.LBB0_587:
	s_add_u32 s90, s52, s4
	s_addc_u32 s91, s53, s5
	s_add_u32 s90, s90, 0x80080
	s_addc_u32 s91, s91, 0
	s_add_u32 s16, s52, s4
	s_addc_u32 s17, s53, s5
	s_add_u32 s16, s16, 0x100
	s_addc_u32 s17, s17, 0
	s_add_u32 s41, s21, s4
	s_addc_u32 s45, s74, s5
	s_add_i32 s51, 0, 0x10000
	s_cmpk_eq_i32 s4, 0xf00
	s_cselect_b32 s39, s61, s17
	s_cselect_b32 s38, s60, s16
	v_add_u32_e32 v156, s51, v157
	s_cselect_b32 s17, s31, s45
	s_cselect_b32 s16, s30, s41
	s_add_i32 s41, 0, 0x14000
	ds_read_b128 v[138:141], v156
	ds_read_b128 v[152:155], v156 offset:1024
	ds_read_b128 v[158:161], v156 offset:2048
	ds_read_b128 v[164:167], v156 offset:3072
	v_add_u32_e32 v156, s41, v157
	ds_read_b128 v[170:173], v156
	ds_read_b128 v[174:177], v156 offset:1024
	ds_read_b128 v[178:181], v156 offset:2048
	ds_read_b128 v[186:189], v156 offset:3072
	s_add_i32 m0, s58, 0xc000
	ds_read_b128 v[190:193], v184
	ds_read_b128 v[194:197], v184 offset:1024
	ds_read_b128 v[204:207], v184 offset:2048
	ds_read_b128 v[208:211], v184 offset:3072
	ds_read_b128 v[212:215], v184 offset:4096
	ds_read_b128 v[216:219], v184 offset:5120
	ds_read_b128 v[220:223], v184 offset:6144
	ds_read_b128 v[224:227], v184 offset:7168
	global_load_lds_dwordx4 v150, s[90:91]
	s_add_i32 m0, s58, 0xe000
	s_nop 0
	global_load_lds_dwordx4 v148, s[90:91]
	s_waitcnt vmcnt(8)
	s_waitcnt lgkmcnt(0)
	s_setprio 1
	s_barrier
	v_mfma_f32_16x16x32_bf16 v[6:9], v[138:141], v[190:193], v[6:9]
	v_mfma_f32_16x16x32_bf16 v[130:133], v[158:161], v[190:193], v[130:133]
	v_mfma_f32_16x16x32_bf16 v[126:129], v[138:141], v[204:207], v[126:129]
	v_mfma_f32_16x16x32_bf16 v[122:125], v[158:161], v[204:207], v[122:125]
	v_mfma_f32_16x16x32_bf16 v[118:121], v[138:141], v[212:215], v[118:121]
	v_mfma_f32_16x16x32_bf16 v[114:117], v[158:161], v[212:215], v[114:117]
	v_mfma_f32_16x16x32_bf16 v[110:113], v[138:141], v[220:223], v[110:113]
	v_mfma_f32_16x16x32_bf16 v[106:109], v[158:161], v[220:223], v[106:109]
	v_mfma_f32_16x16x32_bf16 v[6:9], v[152:155], v[194:197], v[6:9]
	v_mfma_f32_16x16x32_bf16 v[130:133], v[164:167], v[194:197], v[130:133]
	v_mfma_f32_16x16x32_bf16 v[126:129], v[152:155], v[208:211], v[126:129]
	v_mfma_f32_16x16x32_bf16 v[122:125], v[164:167], v[208:211], v[122:125]
	v_mfma_f32_16x16x32_bf16 v[118:121], v[152:155], v[216:219], v[118:121]
	v_mfma_f32_16x16x32_bf16 v[114:117], v[164:167], v[216:219], v[114:117]
	v_mfma_f32_16x16x32_bf16 v[110:113], v[152:155], v[224:227], v[110:113]
	v_mfma_f32_16x16x32_bf16 v[106:109], v[164:167], v[224:227], v[106:109]
	v_mfma_f32_16x16x32_bf16 v[102:105], v[170:173], v[190:193], v[102:105]
	v_mfma_f32_16x16x32_bf16 v[98:101], v[178:181], v[190:193], v[98:101]
	v_mfma_f32_16x16x32_bf16 v[94:97], v[170:173], v[204:207], v[94:97]
	v_mfma_f32_16x16x32_bf16 v[90:93], v[178:181], v[204:207], v[90:93]
	v_mfma_f32_16x16x32_bf16 v[86:89], v[170:173], v[212:215], v[86:89]
	v_mfma_f32_16x16x32_bf16 v[82:85], v[178:181], v[212:215], v[82:85]
	v_mfma_f32_16x16x32_bf16 v[78:81], v[170:173], v[220:223], v[78:81]
	v_mfma_f32_16x16x32_bf16 v[74:77], v[178:181], v[220:223], v[74:77]
	v_mfma_f32_16x16x32_bf16 v[102:105], v[174:177], v[194:197], v[102:105]
	v_mfma_f32_16x16x32_bf16 v[98:101], v[186:189], v[194:197], v[98:101]
	v_mfma_f32_16x16x32_bf16 v[94:97], v[174:177], v[208:211], v[94:97]
	v_mfma_f32_16x16x32_bf16 v[90:93], v[186:189], v[208:211], v[90:93]
	v_mfma_f32_16x16x32_bf16 v[86:89], v[174:177], v[216:219], v[86:89]
	v_mfma_f32_16x16x32_bf16 v[82:85], v[186:189], v[216:219], v[82:85]
	v_mfma_f32_16x16x32_bf16 v[78:81], v[174:177], v[224:227], v[78:81]
	v_mfma_f32_16x16x32_bf16 v[74:77], v[186:189], v[224:227], v[74:77]
	s_barrier
	s_setprio 0
	s_add_i32 s45, s51, s49
	s_mov_b32 m0, s45
	ds_read_b128 v[190:193], v184 offset:16384
	ds_read_b128 v[194:197], v184 offset:17408
	ds_read_b128 v[204:207], v184 offset:18432
	ds_read_b128 v[208:211], v184 offset:19456
	ds_read_b128 v[212:215], v184 offset:20480
	ds_read_b128 v[216:219], v184 offset:21504
	ds_read_b128 v[220:223], v184 offset:22528
	ds_read_b128 v[224:227], v184 offset:23552
	global_load_lds_dwordx4 v0, s[16:17]
	s_add_i32 m0, s45, 0x2000
	s_add_u32 s76, s16, 0x80000
	s_addc_u32 s77, s17, 0
	s_add_i32 s41, s41, s49
	global_load_lds_dwordx4 v144, s[16:17]
	s_mov_b32 m0, s41
	s_add_u32 s92, s38, s96
	s_addc_u32 s93, s39, s97
	global_load_lds_dwordx4 v0, s[76:77]
	s_add_i32 m0, s41, 0x2000
	s_nop 0
	global_load_lds_dwordx4 v144, s[76:77]
	s_mov_b32 m0, s58
	s_nop 0
	global_load_lds_dwordx4 v14, s[38:39]
	s_mov_b32 m0, s59
	s_nop 0
	global_load_lds_dwordx4 v142, s[38:39]
	s_waitcnt vmcnt(8)
	s_waitcnt lgkmcnt(0)
	s_setprio 1
	s_barrier
	v_mfma_f32_16x16x32_bf16 v[70:73], v[138:141], v[190:193], v[70:73]
	v_mfma_f32_16x16x32_bf16 v[66:69], v[158:161], v[190:193], v[66:69]
	v_mfma_f32_16x16x32_bf16 v[62:65], v[138:141], v[204:207], v[62:65]
	v_mfma_f32_16x16x32_bf16 v[58:61], v[158:161], v[204:207], v[58:61]
	v_mfma_f32_16x16x32_bf16 v[54:57], v[138:141], v[212:215], v[54:57]
	v_mfma_f32_16x16x32_bf16 v[50:53], v[158:161], v[212:215], v[50:53]
	v_mfma_f32_16x16x32_bf16 v[46:49], v[138:141], v[220:223], v[46:49]
	v_mfma_f32_16x16x32_bf16 v[42:45], v[158:161], v[220:223], v[42:45]
	v_mfma_f32_16x16x32_bf16 v[70:73], v[152:155], v[194:197], v[70:73]
	v_mfma_f32_16x16x32_bf16 v[66:69], v[164:167], v[194:197], v[66:69]
	v_mfma_f32_16x16x32_bf16 v[62:65], v[152:155], v[208:211], v[62:65]
	v_mfma_f32_16x16x32_bf16 v[58:61], v[164:167], v[208:211], v[58:61]
	v_mfma_f32_16x16x32_bf16 v[54:57], v[152:155], v[216:219], v[54:57]
	v_mfma_f32_16x16x32_bf16 v[50:53], v[164:167], v[216:219], v[50:53]
	v_mfma_f32_16x16x32_bf16 v[46:49], v[152:155], v[224:227], v[46:49]
	v_mfma_f32_16x16x32_bf16 v[42:45], v[164:167], v[224:227], v[42:45]
	v_mfma_f32_16x16x32_bf16 v[38:41], v[170:173], v[190:193], v[38:41]
	v_mfma_f32_16x16x32_bf16 v[34:37], v[178:181], v[190:193], v[34:37]
	v_mfma_f32_16x16x32_bf16 v[30:33], v[170:173], v[204:207], v[30:33]
	v_mfma_f32_16x16x32_bf16 v[26:29], v[178:181], v[204:207], v[26:29]
	v_mfma_f32_16x16x32_bf16 v[22:25], v[170:173], v[212:215], v[22:25]
	v_mfma_f32_16x16x32_bf16 v[18:21], v[178:181], v[212:215], v[18:21]
	v_mfma_f32_16x16x32_bf16 v[10:13], v[170:173], v[220:223], v[10:13]
	v_mfma_f32_16x16x32_bf16 v[2:5], v[178:181], v[220:223], v[2:5]
	v_mfma_f32_16x16x32_bf16 v[38:41], v[174:177], v[194:197], v[38:41]
	v_mfma_f32_16x16x32_bf16 v[34:37], v[186:189], v[194:197], v[34:37]
	v_mfma_f32_16x16x32_bf16 v[30:33], v[174:177], v[208:211], v[30:33]
	v_mfma_f32_16x16x32_bf16 v[26:29], v[186:189], v[208:211], v[26:29]
	v_mfma_f32_16x16x32_bf16 v[22:25], v[174:177], v[216:219], v[22:25]
	v_mfma_f32_16x16x32_bf16 v[18:21], v[186:189], v[216:219], v[18:21]
	v_mfma_f32_16x16x32_bf16 v[10:13], v[174:177], v[224:227], v[10:13]
	v_mfma_f32_16x16x32_bf16 v[2:5], v[186:189], v[224:227], v[2:5]
	s_barrier
	s_setprio 0
	s_add_i32 s41, 0, 0x18000
	v_add_u32_e32 v156, s41, v157
	s_add_i32 s45, 0, 0x1c000
	ds_read_b128 v[138:141], v156
	ds_read_b128 v[152:155], v156 offset:1024
	ds_read_b128 v[158:161], v156 offset:2048
	ds_read_b128 v[164:167], v156 offset:3072
	v_add_u32_e32 v156, s45, v157
	ds_read_b128 v[170:173], v156
	ds_read_b128 v[174:177], v156 offset:1024
	ds_read_b128 v[178:181], v156 offset:2048
	ds_read_b128 v[186:189], v156 offset:3072
	s_add_u32 s38, s38, 0x80000
	s_addc_u32 s39, s39, 0
	s_mov_b32 m0, s62
	ds_read_b128 v[190:193], v184 offset:32768
	ds_read_b128 v[194:197], v184 offset:33792
	ds_read_b128 v[204:207], v184 offset:34816
	ds_read_b128 v[208:211], v184 offset:35840
	ds_read_b128 v[212:215], v184 offset:36864
	ds_read_b128 v[216:219], v184 offset:37888
	ds_read_b128 v[220:223], v184 offset:38912
	ds_read_b128 v[224:227], v184 offset:39936
	global_load_lds_dwordx4 v14, s[38:39]
	s_mov_b32 m0, s63
	s_nop 0
	global_load_lds_dwordx4 v142, s[38:39]
	s_waitcnt vmcnt(8)
	s_waitcnt lgkmcnt(0)
	s_setprio 1
	s_barrier
	v_mfma_f32_16x16x32_bf16 v[6:9], v[138:141], v[190:193], v[6:9]
	v_mfma_f32_16x16x32_bf16 v[130:133], v[158:161], v[190:193], v[130:133]
	v_mfma_f32_16x16x32_bf16 v[126:129], v[138:141], v[204:207], v[126:129]
	v_mfma_f32_16x16x32_bf16 v[122:125], v[158:161], v[204:207], v[122:125]
	v_mfma_f32_16x16x32_bf16 v[118:121], v[138:141], v[212:215], v[118:121]
	v_mfma_f32_16x16x32_bf16 v[114:117], v[158:161], v[212:215], v[114:117]
	v_mfma_f32_16x16x32_bf16 v[110:113], v[138:141], v[220:223], v[110:113]
	v_mfma_f32_16x16x32_bf16 v[106:109], v[158:161], v[220:223], v[106:109]
	v_mfma_f32_16x16x32_bf16 v[6:9], v[152:155], v[194:197], v[6:9]
	v_mfma_f32_16x16x32_bf16 v[130:133], v[164:167], v[194:197], v[130:133]
	v_mfma_f32_16x16x32_bf16 v[126:129], v[152:155], v[208:211], v[126:129]
	v_mfma_f32_16x16x32_bf16 v[122:125], v[164:167], v[208:211], v[122:125]
	v_mfma_f32_16x16x32_bf16 v[118:121], v[152:155], v[216:219], v[118:121]
	v_mfma_f32_16x16x32_bf16 v[114:117], v[164:167], v[216:219], v[114:117]
	v_mfma_f32_16x16x32_bf16 v[110:113], v[152:155], v[224:227], v[110:113]
	v_mfma_f32_16x16x32_bf16 v[106:109], v[164:167], v[224:227], v[106:109]
	v_mfma_f32_16x16x32_bf16 v[102:105], v[170:173], v[190:193], v[102:105]
	v_mfma_f32_16x16x32_bf16 v[98:101], v[178:181], v[190:193], v[98:101]
	v_mfma_f32_16x16x32_bf16 v[94:97], v[170:173], v[204:207], v[94:97]
	v_mfma_f32_16x16x32_bf16 v[90:93], v[178:181], v[204:207], v[90:93]
	v_mfma_f32_16x16x32_bf16 v[86:89], v[170:173], v[212:215], v[86:89]
	v_mfma_f32_16x16x32_bf16 v[82:85], v[178:181], v[212:215], v[82:85]
	v_mfma_f32_16x16x32_bf16 v[78:81], v[170:173], v[220:223], v[78:81]
	v_mfma_f32_16x16x32_bf16 v[74:77], v[178:181], v[220:223], v[74:77]
	v_mfma_f32_16x16x32_bf16 v[102:105], v[174:177], v[194:197], v[102:105]
	v_mfma_f32_16x16x32_bf16 v[98:101], v[186:189], v[194:197], v[98:101]
	v_mfma_f32_16x16x32_bf16 v[94:97], v[174:177], v[208:211], v[94:97]
	v_mfma_f32_16x16x32_bf16 v[90:93], v[186:189], v[208:211], v[90:93]
	v_mfma_f32_16x16x32_bf16 v[86:89], v[174:177], v[216:219], v[86:89]
	v_mfma_f32_16x16x32_bf16 v[82:85], v[186:189], v[216:219], v[82:85]
	v_mfma_f32_16x16x32_bf16 v[78:81], v[174:177], v[224:227], v[78:81]
	v_mfma_f32_16x16x32_bf16 v[74:77], v[186:189], v[224:227], v[74:77]
	s_barrier
	s_setprio 0
	s_add_i32 s38, s41, s49
	s_add_u32 s90, s16, s96
	s_addc_u32 s91, s17, s97
	s_mov_b32 m0, s38
	ds_read_b128 v[190:193], v184 offset:49152
	ds_read_b128 v[194:197], v184 offset:50176
	ds_read_b128 v[204:207], v184 offset:51200
	ds_read_b128 v[208:211], v184 offset:52224
	ds_read_b128 v[212:215], v184 offset:53248
	ds_read_b128 v[216:219], v184 offset:54272
	ds_read_b128 v[220:223], v184 offset:55296
	ds_read_b128 v[224:227], v184 offset:56320
	global_load_lds_dwordx4 v0, s[90:91]
	s_add_i32 m0, s38, 0x2000
	s_add_u32 s16, s16, 0x80080
	s_addc_u32 s17, s17, 0
	s_add_i32 s38, s45, s49
	global_load_lds_dwordx4 v144, s[90:91]
	s_mov_b32 m0, s38
	s_nop 0
	global_load_lds_dwordx4 v0, s[16:17]
	s_add_i32 m0, s38, 0x2000
	s_nop 0
	global_load_lds_dwordx4 v144, s[16:17]
	s_mov_b32 m0, s68
	s_nop 0
	global_load_lds_dwordx4 v14, s[92:93]
	s_mov_b32 m0, s69
	s_nop 0
	global_load_lds_dwordx4 v142, s[92:93]
	s_waitcnt vmcnt(8)
	s_waitcnt lgkmcnt(0)
	s_setprio 1
	s_barrier
	v_mfma_f32_16x16x32_bf16 v[70:73], v[138:141], v[190:193], v[70:73]
	v_mfma_f32_16x16x32_bf16 v[66:69], v[158:161], v[190:193], v[66:69]
	v_mfma_f32_16x16x32_bf16 v[62:65], v[138:141], v[204:207], v[62:65]
	v_mfma_f32_16x16x32_bf16 v[58:61], v[158:161], v[204:207], v[58:61]
	v_mfma_f32_16x16x32_bf16 v[54:57], v[138:141], v[212:215], v[54:57]
	v_mfma_f32_16x16x32_bf16 v[50:53], v[158:161], v[212:215], v[50:53]
	v_mfma_f32_16x16x32_bf16 v[46:49], v[138:141], v[220:223], v[46:49]
	v_mfma_f32_16x16x32_bf16 v[42:45], v[158:161], v[220:223], v[42:45]
	v_mfma_f32_16x16x32_bf16 v[70:73], v[152:155], v[194:197], v[70:73]
	v_mfma_f32_16x16x32_bf16 v[66:69], v[164:167], v[194:197], v[66:69]
	v_mfma_f32_16x16x32_bf16 v[62:65], v[152:155], v[208:211], v[62:65]
	v_mfma_f32_16x16x32_bf16 v[58:61], v[164:167], v[208:211], v[58:61]
	v_mfma_f32_16x16x32_bf16 v[54:57], v[152:155], v[216:219], v[54:57]
	v_mfma_f32_16x16x32_bf16 v[50:53], v[164:167], v[216:219], v[50:53]
	v_mfma_f32_16x16x32_bf16 v[46:49], v[152:155], v[224:227], v[46:49]
	v_mfma_f32_16x16x32_bf16 v[42:45], v[164:167], v[224:227], v[42:45]
	v_mfma_f32_16x16x32_bf16 v[38:41], v[170:173], v[190:193], v[38:41]
	v_mfma_f32_16x16x32_bf16 v[34:37], v[178:181], v[190:193], v[34:37]
	v_mfma_f32_16x16x32_bf16 v[30:33], v[170:173], v[204:207], v[30:33]
	v_mfma_f32_16x16x32_bf16 v[26:29], v[178:181], v[204:207], v[26:29]
	v_mfma_f32_16x16x32_bf16 v[22:25], v[170:173], v[212:215], v[22:25]
	v_mfma_f32_16x16x32_bf16 v[18:21], v[178:181], v[212:215], v[18:21]
	v_mfma_f32_16x16x32_bf16 v[10:13], v[170:173], v[220:223], v[10:13]
	v_mfma_f32_16x16x32_bf16 v[2:5], v[178:181], v[220:223], v[2:5]
	v_mfma_f32_16x16x32_bf16 v[38:41], v[174:177], v[194:197], v[38:41]
	v_mfma_f32_16x16x32_bf16 v[34:37], v[186:189], v[194:197], v[34:37]
	v_mfma_f32_16x16x32_bf16 v[30:33], v[174:177], v[208:211], v[30:33]
	v_mfma_f32_16x16x32_bf16 v[26:29], v[186:189], v[208:211], v[26:29]
	v_mfma_f32_16x16x32_bf16 v[22:25], v[174:177], v[216:219], v[22:25]
	v_mfma_f32_16x16x32_bf16 v[18:21], v[186:189], v[216:219], v[18:21]
	v_mfma_f32_16x16x32_bf16 v[10:13], v[174:177], v[224:227], v[10:13]
	v_mfma_f32_16x16x32_bf16 v[2:5], v[186:189], v[224:227], v[2:5]
	s_barrier
	s_setprio 0
	s_add_i32 s40, s40, 2
	s_add_u32 s4, s4, 0x100
	s_addc_u32 s5, s5, 0
	s_cmp_gt_u32 s40, 29
	s_cbranch_scc0 .LBB0_587
	s_and_b64 vcc, exec, s[26:27]
	s_cbranch_vccz .LBB0_590
	s_barrier

.LBB0_728:
	s_add_u32 s86, s38, s8
	s_addc_u32 s87, s39, s9
	s_add_u32 s86, s86, 0x158080
	s_addc_u32 s87, s87, 0
	s_add_u32 s16, s38, s8
	s_addc_u32 s17, s39, s9
	s_add_u32 s16, s16, 0x100
	s_addc_u32 s17, s17, 0
	s_add_u32 s34, s41, s8
	s_addc_u32 s64, s10, s9
	s_add_i32 s65, 0, 0x10000
	s_cmpk_eq_i32 s8, 0x2a00
	s_cselect_b32 s49, s53, s17
	s_cselect_b32 s48, s52, s16
	s_cselect_b32 s17, s61, s64
	s_cselect_b32 s16, s60, s34
	s_add_i32 s34, 0, 0x14000
	v_add_u32_e32 v150, s65, v234
	v_add_u32_e32 v166, s34, v234
	ds_read_b128 v[138:141], v150
	ds_read_b128 v[142:145], v150 offset:1024
	ds_read_b128 v[146:149], v150 offset:2048
	ds_read_b128 v[150:153], v150 offset:3072
	ds_read_b128 v[154:157], v166
	ds_read_b128 v[158:161], v166 offset:1024
	ds_read_b128 v[162:165], v166 offset:2048
	ds_read_b128 v[166:169], v166 offset:3072
	s_add_i32 m0, s67, 0xc000
	ds_read_b128 v[170:173], v238
	ds_read_b128 v[174:177], v238 offset:1024
	ds_read_b128 v[178:181], v238 offset:2048
	ds_read_b128 v[182:185], v238 offset:3072
	ds_read_b128 v[186:189], v238 offset:4096
	ds_read_b128 v[190:193], v238 offset:5120
	ds_read_b128 v[194:197], v238 offset:6144
	ds_read_b128 v[208:211], v238 offset:7168
	global_load_lds_dwordx4 v206, s[86:87]
	s_add_i32 m0, s67, 0xe000
	s_nop 0
	global_load_lds_dwordx4 v204, s[86:87]
	s_waitcnt vmcnt(8)
	s_waitcnt lgkmcnt(0)
	s_barrier
	s_setprio 1
	s_waitcnt lgkmcnt(0)
	v_mfma_f32_16x16x32_bf16 v[6:9], v[138:141], v[170:173], v[6:9]
	v_mfma_f32_16x16x32_bf16 v[130:133], v[146:149], v[170:173], v[130:133]
	v_mfma_f32_16x16x32_bf16 v[126:129], v[138:141], v[178:181], v[126:129]
	v_mfma_f32_16x16x32_bf16 v[122:125], v[146:149], v[178:181], v[122:125]
	v_mfma_f32_16x16x32_bf16 v[118:121], v[138:141], v[186:189], v[118:121]
	v_mfma_f32_16x16x32_bf16 v[114:117], v[146:149], v[186:189], v[114:117]
	v_mfma_f32_16x16x32_bf16 v[110:113], v[138:141], v[194:197], v[110:113]
	v_mfma_f32_16x16x32_bf16 v[106:109], v[146:149], v[194:197], v[106:109]
	v_mfma_f32_16x16x32_bf16 v[6:9], v[142:145], v[174:177], v[6:9]
	v_mfma_f32_16x16x32_bf16 v[130:133], v[150:153], v[174:177], v[130:133]
	v_mfma_f32_16x16x32_bf16 v[126:129], v[142:145], v[182:185], v[126:129]
	v_mfma_f32_16x16x32_bf16 v[122:125], v[150:153], v[182:185], v[122:125]
	v_mfma_f32_16x16x32_bf16 v[118:121], v[142:145], v[190:193], v[118:121]
	v_mfma_f32_16x16x32_bf16 v[114:117], v[150:153], v[190:193], v[114:117]
	v_mfma_f32_16x16x32_bf16 v[110:113], v[142:145], v[208:211], v[110:113]
	v_mfma_f32_16x16x32_bf16 v[106:109], v[150:153], v[208:211], v[106:109]
	s_setprio 0
	s_setprio 1
	v_mfma_f32_16x16x32_bf16 v[102:105], v[154:157], v[170:173], v[102:105]
	v_mfma_f32_16x16x32_bf16 v[98:101], v[162:165], v[170:173], v[98:101]
	v_mfma_f32_16x16x32_bf16 v[94:97], v[154:157], v[178:181], v[94:97]
	v_mfma_f32_16x16x32_bf16 v[90:93], v[162:165], v[178:181], v[90:93]
	v_mfma_f32_16x16x32_bf16 v[86:89], v[154:157], v[186:189], v[86:89]
	v_mfma_f32_16x16x32_bf16 v[82:85], v[162:165], v[186:189], v[82:85]
	v_mfma_f32_16x16x32_bf16 v[78:81], v[154:157], v[194:197], v[78:81]
	v_mfma_f32_16x16x32_bf16 v[74:77], v[162:165], v[194:197], v[74:77]
	v_mfma_f32_16x16x32_bf16 v[102:105], v[158:161], v[174:177], v[102:105]
	v_mfma_f32_16x16x32_bf16 v[98:101], v[166:169], v[174:177], v[98:101]
	v_mfma_f32_16x16x32_bf16 v[94:97], v[158:161], v[182:185], v[94:97]
	v_mfma_f32_16x16x32_bf16 v[90:93], v[166:169], v[182:185], v[90:93]
	v_mfma_f32_16x16x32_bf16 v[86:89], v[158:161], v[190:193], v[86:89]
	v_mfma_f32_16x16x32_bf16 v[82:85], v[166:169], v[190:193], v[82:85]
	v_mfma_f32_16x16x32_bf16 v[78:81], v[158:161], v[208:211], v[78:81]
	v_mfma_f32_16x16x32_bf16 v[74:77], v[166:169], v[208:211], v[74:77]
	s_setprio 0
	s_barrier
	s_add_i32 s64, s65, s66
	s_mov_b32 m0, s64
	ds_read_b128 v[170:173], v238 offset:16384
	ds_read_b128 v[174:177], v238 offset:17408
	ds_read_b128 v[178:181], v238 offset:18432
	ds_read_b128 v[182:185], v238 offset:19456
	ds_read_b128 v[186:189], v238 offset:20480
	ds_read_b128 v[190:193], v238 offset:21504
	ds_read_b128 v[194:197], v238 offset:22528
	ds_read_b128 v[208:211], v238 offset:23552
	global_load_lds_dwordx4 v0, s[16:17]
	s_add_i32 m0, s64, 0x2000
	s_add_u32 s64, s16, 0x158000
	s_addc_u32 s65, s17, 0
	s_add_i32 s34, s34, s66
	global_load_lds_dwordx4 v14, s[16:17]
	s_mov_b32 m0, s34
	s_add_u32 s98, s48, s96
	s_addc_u32 s99, s49, s97
	global_load_lds_dwordx4 v0, s[64:65]
	s_add_i32 m0, s34, 0x2000
	s_nop 0
	global_load_lds_dwordx4 v14, s[64:65]
	s_mov_b32 m0, s67
	s_nop 0
	global_load_lds_dwordx4 v0, s[48:49]
	s_mov_b32 m0, s68
	s_nop 0
	global_load_lds_dwordx4 v14, s[48:49]
	s_waitcnt vmcnt(8)
	s_waitcnt lgkmcnt(0)
	s_barrier
	s_setprio 1
	s_waitcnt lgkmcnt(0)
	v_mfma_f32_16x16x32_bf16 v[70:73], v[138:141], v[170:173], v[70:73]
	v_mfma_f32_16x16x32_bf16 v[66:69], v[146:149], v[170:173], v[66:69]
	v_mfma_f32_16x16x32_bf16 v[62:65], v[138:141], v[178:181], v[62:65]
	v_mfma_f32_16x16x32_bf16 v[58:61], v[146:149], v[178:181], v[58:61]
	v_mfma_f32_16x16x32_bf16 v[54:57], v[138:141], v[186:189], v[54:57]
	v_mfma_f32_16x16x32_bf16 v[50:53], v[146:149], v[186:189], v[50:53]
	v_mfma_f32_16x16x32_bf16 v[46:49], v[138:141], v[194:197], v[46:49]
	v_mfma_f32_16x16x32_bf16 v[42:45], v[146:149], v[194:197], v[42:45]
	v_mfma_f32_16x16x32_bf16 v[70:73], v[142:145], v[174:177], v[70:73]
	v_mfma_f32_16x16x32_bf16 v[66:69], v[150:153], v[174:177], v[66:69]
	v_mfma_f32_16x16x32_bf16 v[62:65], v[142:145], v[182:185], v[62:65]
	v_mfma_f32_16x16x32_bf16 v[58:61], v[150:153], v[182:185], v[58:61]
	v_mfma_f32_16x16x32_bf16 v[54:57], v[142:145], v[190:193], v[54:57]
	v_mfma_f32_16x16x32_bf16 v[50:53], v[150:153], v[190:193], v[50:53]
	v_mfma_f32_16x16x32_bf16 v[46:49], v[142:145], v[208:211], v[46:49]
	v_mfma_f32_16x16x32_bf16 v[42:45], v[150:153], v[208:211], v[42:45]
	s_setprio 0
	s_setprio 1
	v_mfma_f32_16x16x32_bf16 v[38:41], v[154:157], v[170:173], v[38:41]
	v_mfma_f32_16x16x32_bf16 v[34:37], v[162:165], v[170:173], v[34:37]
	v_mfma_f32_16x16x32_bf16 v[30:33], v[154:157], v[178:181], v[30:33]
	v_mfma_f32_16x16x32_bf16 v[26:29], v[162:165], v[178:181], v[26:29]
	v_mfma_f32_16x16x32_bf16 v[22:25], v[154:157], v[186:189], v[22:25]
	v_mfma_f32_16x16x32_bf16 v[18:21], v[162:165], v[186:189], v[18:21]
	v_mfma_f32_16x16x32_bf16 v[10:13], v[154:157], v[194:197], v[10:13]
	v_mfma_f32_16x16x32_bf16 v[2:5], v[162:165], v[194:197], v[2:5]
	v_mfma_f32_16x16x32_bf16 v[38:41], v[158:161], v[174:177], v[38:41]
	v_mfma_f32_16x16x32_bf16 v[34:37], v[166:169], v[174:177], v[34:37]
	v_mfma_f32_16x16x32_bf16 v[30:33], v[158:161], v[182:185], v[30:33]
	v_mfma_f32_16x16x32_bf16 v[26:29], v[166:169], v[182:185], v[26:29]
	v_mfma_f32_16x16x32_bf16 v[22:25], v[158:161], v[190:193], v[22:25]
	v_mfma_f32_16x16x32_bf16 v[18:21], v[166:169], v[190:193], v[18:21]
	v_mfma_f32_16x16x32_bf16 v[10:13], v[158:161], v[208:211], v[10:13]
	v_mfma_f32_16x16x32_bf16 v[2:5], v[166:169], v[208:211], v[2:5]
	s_setprio 0
	s_barrier
	s_add_i32 s34, 0, 0x18000
	s_add_i32 s64, 0, 0x1c000
	v_add_u32_e32 v150, s34, v234
	v_add_u32_e32 v166, s64, v234
	ds_read_b128 v[138:141], v150
	ds_read_b128 v[142:145], v150 offset:1024
	ds_read_b128 v[146:149], v150 offset:2048
	ds_read_b128 v[150:153], v150 offset:3072
	ds_read_b128 v[154:157], v166
	ds_read_b128 v[158:161], v166 offset:1024
	ds_read_b128 v[162:165], v166 offset:2048
	ds_read_b128 v[166:169], v166 offset:3072
	s_add_u32 s48, s48, 0x158000
	s_addc_u32 s49, s49, 0
	s_mov_b32 m0, s69
	ds_read_b128 v[170:173], v238 offset:32768
	ds_read_b128 v[174:177], v238 offset:33792
	ds_read_b128 v[178:181], v238 offset:34816
	ds_read_b128 v[182:185], v238 offset:35840
	ds_read_b128 v[186:189], v238 offset:36864
	ds_read_b128 v[190:193], v238 offset:37888
	ds_read_b128 v[194:197], v238 offset:38912
	ds_read_b128 v[208:211], v238 offset:39936
	global_load_lds_dwordx4 v0, s[48:49]
	s_mov_b32 m0, s70
	s_nop 0
	global_load_lds_dwordx4 v14, s[48:49]
	s_waitcnt vmcnt(8)
	s_waitcnt lgkmcnt(0)
	s_barrier
	s_setprio 1
	s_waitcnt lgkmcnt(0)
	v_mfma_f32_16x16x32_bf16 v[6:9], v[138:141], v[170:173], v[6:9]
	v_mfma_f32_16x16x32_bf16 v[130:133], v[146:149], v[170:173], v[130:133]
	v_mfma_f32_16x16x32_bf16 v[126:129], v[138:141], v[178:181], v[126:129]
	v_mfma_f32_16x16x32_bf16 v[122:125], v[146:149], v[178:181], v[122:125]
	v_mfma_f32_16x16x32_bf16 v[118:121], v[138:141], v[186:189], v[118:121]
	v_mfma_f32_16x16x32_bf16 v[114:117], v[146:149], v[186:189], v[114:117]
	v_mfma_f32_16x16x32_bf16 v[110:113], v[138:141], v[194:197], v[110:113]
	v_mfma_f32_16x16x32_bf16 v[106:109], v[146:149], v[194:197], v[106:109]
	v_mfma_f32_16x16x32_bf16 v[6:9], v[142:145], v[174:177], v[6:9]
	v_mfma_f32_16x16x32_bf16 v[130:133], v[150:153], v[174:177], v[130:133]
	v_mfma_f32_16x16x32_bf16 v[126:129], v[142:145], v[182:185], v[126:129]
	v_mfma_f32_16x16x32_bf16 v[122:125], v[150:153], v[182:185], v[122:125]
	v_mfma_f32_16x16x32_bf16 v[118:121], v[142:145], v[190:193], v[118:121]
	v_mfma_f32_16x16x32_bf16 v[114:117], v[150:153], v[190:193], v[114:117]
	v_mfma_f32_16x16x32_bf16 v[110:113], v[142:145], v[208:211], v[110:113]
	v_mfma_f32_16x16x32_bf16 v[106:109], v[150:153], v[208:211], v[106:109]
	s_setprio 0
	s_setprio 1
	v_mfma_f32_16x16x32_bf16 v[102:105], v[154:157], v[170:173], v[102:105]
	v_mfma_f32_16x16x32_bf16 v[98:101], v[162:165], v[170:173], v[98:101]
	v_mfma_f32_16x16x32_bf16 v[94:97], v[154:157], v[178:181], v[94:97]
	v_mfma_f32_16x16x32_bf16 v[90:93], v[162:165], v[178:181], v[90:93]
	v_mfma_f32_16x16x32_bf16 v[86:89], v[154:157], v[186:189], v[86:89]
	v_mfma_f32_16x16x32_bf16 v[82:85], v[162:165], v[186:189], v[82:85]
	v_mfma_f32_16x16x32_bf16 v[78:81], v[154:157], v[194:197], v[78:81]
	v_mfma_f32_16x16x32_bf16 v[74:77], v[162:165], v[194:197], v[74:77]
	v_mfma_f32_16x16x32_bf16 v[102:105], v[158:161], v[174:177], v[102:105]
	v_mfma_f32_16x16x32_bf16 v[98:101], v[166:169], v[174:177], v[98:101]
	v_mfma_f32_16x16x32_bf16 v[94:97], v[158:161], v[182:185], v[94:97]
	v_mfma_f32_16x16x32_bf16 v[90:93], v[166:169], v[182:185], v[90:93]
	v_mfma_f32_16x16x32_bf16 v[86:89], v[158:161], v[190:193], v[86:89]
	v_mfma_f32_16x16x32_bf16 v[82:85], v[166:169], v[190:193], v[82:85]
	v_mfma_f32_16x16x32_bf16 v[78:81], v[158:161], v[208:211], v[78:81]
	v_mfma_f32_16x16x32_bf16 v[74:77], v[166:169], v[208:211], v[74:77]
	s_setprio 0
	s_barrier
	s_add_i32 s34, s34, s66
	s_add_u32 s86, s16, s96
	s_addc_u32 s87, s17, s97
	s_mov_b32 m0, s34
	ds_read_b128 v[170:173], v238 offset:49152
	ds_read_b128 v[174:177], v238 offset:50176
	ds_read_b128 v[178:181], v238 offset:51200
	ds_read_b128 v[182:185], v238 offset:52224
	ds_read_b128 v[186:189], v238 offset:53248
	ds_read_b128 v[190:193], v238 offset:54272
	ds_read_b128 v[194:197], v238 offset:55296
	ds_read_b128 v[208:211], v238 offset:56320
	global_load_lds_dwordx4 v0, s[86:87]
	s_add_i32 m0, s34, 0x2000
	s_add_u32 s16, s16, 0x158080
	s_addc_u32 s17, s17, 0
	s_add_i32 s34, s64, s66
	global_load_lds_dwordx4 v14, s[86:87]
	s_mov_b32 m0, s34
	s_nop 0
	global_load_lds_dwordx4 v0, s[16:17]
	s_add_i32 m0, s34, 0x2000
	s_nop 0
	global_load_lds_dwordx4 v14, s[16:17]
	s_mov_b32 m0, s76
	s_nop 0
	global_load_lds_dwordx4 v0, s[98:99]
	s_mov_b32 m0, s77
	s_nop 0
	global_load_lds_dwordx4 v14, s[98:99]
	s_waitcnt vmcnt(8)
	s_waitcnt lgkmcnt(0)
	s_barrier
	s_setprio 1
	s_waitcnt lgkmcnt(0)
	v_mfma_f32_16x16x32_bf16 v[70:73], v[138:141], v[170:173], v[70:73]
	v_mfma_f32_16x16x32_bf16 v[66:69], v[146:149], v[170:173], v[66:69]
	v_mfma_f32_16x16x32_bf16 v[62:65], v[138:141], v[178:181], v[62:65]
	v_mfma_f32_16x16x32_bf16 v[58:61], v[146:149], v[178:181], v[58:61]
	v_mfma_f32_16x16x32_bf16 v[54:57], v[138:141], v[186:189], v[54:57]
	v_mfma_f32_16x16x32_bf16 v[50:53], v[146:149], v[186:189], v[50:53]
	v_mfma_f32_16x16x32_bf16 v[46:49], v[138:141], v[194:197], v[46:49]
	v_mfma_f32_16x16x32_bf16 v[42:45], v[146:149], v[194:197], v[42:45]
	v_mfma_f32_16x16x32_bf16 v[70:73], v[142:145], v[174:177], v[70:73]
	v_mfma_f32_16x16x32_bf16 v[66:69], v[150:153], v[174:177], v[66:69]
	v_mfma_f32_16x16x32_bf16 v[62:65], v[142:145], v[182:185], v[62:65]
	v_mfma_f32_16x16x32_bf16 v[58:61], v[150:153], v[182:185], v[58:61]
	v_mfma_f32_16x16x32_bf16 v[54:57], v[142:145], v[190:193], v[54:57]
	v_mfma_f32_16x16x32_bf16 v[50:53], v[150:153], v[190:193], v[50:53]
	v_mfma_f32_16x16x32_bf16 v[46:49], v[142:145], v[208:211], v[46:49]
	v_mfma_f32_16x16x32_bf16 v[42:45], v[150:153], v[208:211], v[42:45]
	s_setprio 0
	s_setprio 1
	v_mfma_f32_16x16x32_bf16 v[38:41], v[154:157], v[170:173], v[38:41]
	v_mfma_f32_16x16x32_bf16 v[34:37], v[162:165], v[170:173], v[34:37]
	v_mfma_f32_16x16x32_bf16 v[30:33], v[154:157], v[178:181], v[30:33]
	v_mfma_f32_16x16x32_bf16 v[26:29], v[162:165], v[178:181], v[26:29]
	v_mfma_f32_16x16x32_bf16 v[22:25], v[154:157], v[186:189], v[22:25]
	v_mfma_f32_16x16x32_bf16 v[18:21], v[162:165], v[186:189], v[18:21]
	v_mfma_f32_16x16x32_bf16 v[10:13], v[154:157], v[194:197], v[10:13]
	v_mfma_f32_16x16x32_bf16 v[2:5], v[162:165], v[194:197], v[2:5]
	v_mfma_f32_16x16x32_bf16 v[38:41], v[158:161], v[174:177], v[38:41]
	v_mfma_f32_16x16x32_bf16 v[34:37], v[166:169], v[174:177], v[34:37]
	v_mfma_f32_16x16x32_bf16 v[30:33], v[158:161], v[182:185], v[30:33]
	v_mfma_f32_16x16x32_bf16 v[26:29], v[166:169], v[182:185], v[26:29]
	v_mfma_f32_16x16x32_bf16 v[22:25], v[158:161], v[190:193], v[22:25]
	v_mfma_f32_16x16x32_bf16 v[18:21], v[166:169], v[190:193], v[18:21]
	v_mfma_f32_16x16x32_bf16 v[10:13], v[158:161], v[208:211], v[10:13]
	v_mfma_f32_16x16x32_bf16 v[2:5], v[166:169], v[208:211], v[2:5]
	s_setprio 0
	s_barrier
	s_add_i32 s11, s11, 2
	s_add_u32 s8, s8, 0x100
	s_addc_u32 s9, s9, 0
	s_cmpk_gt_u32 s11, 0x53
	s_cbranch_scc0 .LBB0_728
	s_and_b64 vcc, exec, s[28:29]
	s_cbranch_vccz .LBB0_731
	s_barrier

.LBB0_1045:
	s_add_u32 s46, s6, 0xfff80080
	s_addc_u32 s47, s7, -1
	s_add_i32 s52, 0, 0x10000
	s_cmp_eq_u32 s41, 28
	s_cselect_b32 s49, s9, s47
	s_cselect_b32 s48, s29, s46
	v_add_u32_e32 v0, s52, v149
	s_cselect_b32 s47, s31, s40
	s_cselect_b32 s46, s34, s39
	s_add_i32 s60, 0, 0x14000
	ds_read_b128 v[134:137], v0
	ds_read_b128 v[138:141], v0 offset:1024
	ds_read_b128 v[160:163], v0 offset:2048
	ds_read_b128 v[164:167], v0 offset:3072
	v_add_u32_e32 v0, s60, v149
	ds_read_b128 v[168:171], v0
	ds_read_b128 v[172:175], v0 offset:1024
	ds_read_b128 v[176:179], v0 offset:2048
	ds_read_b128 v[188:191], v0 offset:3072
	s_add_i32 m0, s63, 0xc000
	ds_read_b128 v[192:195], v186
	ds_read_b128 v[204:207], v186 offset:1024
	ds_read_b128 v[208:211], v186 offset:2048
	ds_read_b128 v[212:215], v186 offset:3072
	ds_read_b128 v[216:219], v186 offset:4096
	ds_read_b128 v[220:223], v186 offset:5120
	ds_read_b128 v[224:227], v186 offset:6144
	ds_read_b128 v[234:237], v186 offset:7168
	global_load_lds_dwordx4 v158, s[6:7]
	s_add_i32 m0, s63, 0xe000
	s_nop 0
	global_load_lds_dwordx4 v156, s[6:7]
	s_waitcnt vmcnt(8)
	s_waitcnt lgkmcnt(0)
	s_barrier
	s_setprio 1
	s_waitcnt lgkmcnt(0)
	v_mfma_f32_16x16x32_bf16 v[130:133], v[134:137], v[192:195], v[130:133]
	v_mfma_f32_16x16x32_bf16 v[126:129], v[160:163], v[192:195], v[126:129]
	v_mfma_f32_16x16x32_bf16 v[114:117], v[134:137], v[208:211], v[114:117]
	v_mfma_f32_16x16x32_bf16 v[110:113], v[160:163], v[208:211], v[110:113]
	v_mfma_f32_16x16x32_bf16 v[98:101], v[134:137], v[216:219], v[98:101]
	v_mfma_f32_16x16x32_bf16 v[94:97], v[160:163], v[216:219], v[94:97]
	v_mfma_f32_16x16x32_bf16 v[82:85], v[134:137], v[224:227], v[82:85]
	v_mfma_f32_16x16x32_bf16 v[78:81], v[160:163], v[224:227], v[78:81]
	v_mfma_f32_16x16x32_bf16 v[130:133], v[138:141], v[204:207], v[130:133]
	v_mfma_f32_16x16x32_bf16 v[126:129], v[164:167], v[204:207], v[126:129]
	v_mfma_f32_16x16x32_bf16 v[114:117], v[138:141], v[212:215], v[114:117]
	v_mfma_f32_16x16x32_bf16 v[110:113], v[164:167], v[212:215], v[110:113]
	v_mfma_f32_16x16x32_bf16 v[98:101], v[138:141], v[220:223], v[98:101]
	v_mfma_f32_16x16x32_bf16 v[94:97], v[164:167], v[220:223], v[94:97]
	v_mfma_f32_16x16x32_bf16 v[82:85], v[138:141], v[234:237], v[82:85]
	v_mfma_f32_16x16x32_bf16 v[78:81], v[164:167], v[234:237], v[78:81]
	s_setprio 0
	s_setprio 1
	v_mfma_f32_16x16x32_bf16 v[122:125], v[168:171], v[192:195], v[122:125]
	v_mfma_f32_16x16x32_bf16 v[118:121], v[176:179], v[192:195], v[118:121]
	v_mfma_f32_16x16x32_bf16 v[106:109], v[168:171], v[208:211], v[106:109]
	v_mfma_f32_16x16x32_bf16 v[102:105], v[176:179], v[208:211], v[102:105]
	v_mfma_f32_16x16x32_bf16 v[90:93], v[168:171], v[216:219], v[90:93]
	v_mfma_f32_16x16x32_bf16 v[86:89], v[176:179], v[216:219], v[86:89]
	v_mfma_f32_16x16x32_bf16 v[74:77], v[168:171], v[224:227], v[74:77]
	v_mfma_f32_16x16x32_bf16 v[70:73], v[176:179], v[224:227], v[70:73]
	v_mfma_f32_16x16x32_bf16 v[122:125], v[172:175], v[204:207], v[122:125]
	v_mfma_f32_16x16x32_bf16 v[118:121], v[188:191], v[204:207], v[118:121]
	v_mfma_f32_16x16x32_bf16 v[106:109], v[172:175], v[212:215], v[106:109]
	v_mfma_f32_16x16x32_bf16 v[102:105], v[188:191], v[212:215], v[102:105]
	v_mfma_f32_16x16x32_bf16 v[90:93], v[172:175], v[220:223], v[90:93]
	v_mfma_f32_16x16x32_bf16 v[86:89], v[188:191], v[220:223], v[86:89]
	v_mfma_f32_16x16x32_bf16 v[74:77], v[172:175], v[234:237], v[74:77]
	v_mfma_f32_16x16x32_bf16 v[70:73], v[188:191], v[234:237], v[70:73]
	s_setprio 0
	s_barrier
	s_add_i32 s52, s52, s56
	s_mov_b32 m0, s52
	ds_read_b128 v[192:195], v186 offset:16384
	ds_read_b128 v[204:207], v186 offset:17408
	ds_read_b128 v[208:211], v186 offset:18432
	ds_read_b128 v[212:215], v186 offset:19456
	ds_read_b128 v[216:219], v186 offset:20480
	ds_read_b128 v[220:223], v186 offset:21504
	ds_read_b128 v[224:227], v186 offset:22528
	ds_read_b128 v[234:237], v186 offset:23552
	global_load_lds_dwordx4 v142, s[46:47]
	s_add_i32 m0, s52, 0x2000
	s_add_u32 s52, s46, 0x80000
	s_addc_u32 s53, s47, 0
	s_add_i32 s60, s60, s56
	global_load_lds_dwordx4 v146, s[46:47]
	s_mov_b32 m0, s60
	s_add_u32 s98, s48, s96
	s_addc_u32 s99, s49, s97
	global_load_lds_dwordx4 v142, s[52:53]
	s_add_i32 m0, s60, 0x2000
	s_nop 0
	global_load_lds_dwordx4 v146, s[52:53]
	s_mov_b32 m0, s63
	s_nop 0
	global_load_lds_dwordx4 v14, s[48:49]
	s_mov_b32 m0, s66
	s_nop 0
	global_load_lds_dwordx4 v144, s[48:49]
	s_waitcnt vmcnt(8)
	s_waitcnt lgkmcnt(0)
	s_barrier
	s_setprio 1
	s_waitcnt lgkmcnt(0)
	v_mfma_f32_16x16x32_bf16 v[66:69], v[134:137], v[192:195], v[66:69]
	v_mfma_f32_16x16x32_bf16 v[62:65], v[160:163], v[192:195], v[62:65]
	v_mfma_f32_16x16x32_bf16 v[50:53], v[134:137], v[208:211], v[50:53]
	v_mfma_f32_16x16x32_bf16 v[46:49], v[160:163], v[208:211], v[46:49]
	v_mfma_f32_16x16x32_bf16 v[34:37], v[134:137], v[216:219], v[34:37]
	v_mfma_f32_16x16x32_bf16 v[30:33], v[160:163], v[216:219], v[30:33]
	v_mfma_f32_16x16x32_bf16 v[18:21], v[134:137], v[224:227], v[18:21]
	v_mfma_f32_16x16x32_bf16 v[10:13], v[160:163], v[224:227], v[10:13]
	v_mfma_f32_16x16x32_bf16 v[66:69], v[138:141], v[204:207], v[66:69]
	v_mfma_f32_16x16x32_bf16 v[62:65], v[164:167], v[204:207], v[62:65]
	v_mfma_f32_16x16x32_bf16 v[50:53], v[138:141], v[212:215], v[50:53]
	v_mfma_f32_16x16x32_bf16 v[46:49], v[164:167], v[212:215], v[46:49]
	v_mfma_f32_16x16x32_bf16 v[34:37], v[138:141], v[220:223], v[34:37]
	v_mfma_f32_16x16x32_bf16 v[30:33], v[164:167], v[220:223], v[30:33]
	v_mfma_f32_16x16x32_bf16 v[18:21], v[138:141], v[234:237], v[18:21]
	v_mfma_f32_16x16x32_bf16 v[10:13], v[164:167], v[234:237], v[10:13]
	s_setprio 0
	s_setprio 1
	v_mfma_f32_16x16x32_bf16 v[58:61], v[168:171], v[192:195], v[58:61]
	v_mfma_f32_16x16x32_bf16 v[54:57], v[176:179], v[192:195], v[54:57]
	v_mfma_f32_16x16x32_bf16 v[42:45], v[168:171], v[208:211], v[42:45]
	v_mfma_f32_16x16x32_bf16 v[38:41], v[176:179], v[208:211], v[38:41]
	v_mfma_f32_16x16x32_bf16 v[26:29], v[168:171], v[216:219], v[26:29]
	v_mfma_f32_16x16x32_bf16 v[22:25], v[176:179], v[216:219], v[22:25]
	v_mfma_f32_16x16x32_bf16 v[6:9], v[168:171], v[224:227], v[6:9]
	v_mfma_f32_16x16x32_bf16 v[2:5], v[176:179], v[224:227], v[2:5]
	v_mfma_f32_16x16x32_bf16 v[58:61], v[172:175], v[204:207], v[58:61]
	v_mfma_f32_16x16x32_bf16 v[54:57], v[188:191], v[204:207], v[54:57]
	v_mfma_f32_16x16x32_bf16 v[42:45], v[172:175], v[212:215], v[42:45]
	v_mfma_f32_16x16x32_bf16 v[38:41], v[188:191], v[212:215], v[38:41]
	v_mfma_f32_16x16x32_bf16 v[26:29], v[172:175], v[220:223], v[26:29]
	v_mfma_f32_16x16x32_bf16 v[22:25], v[188:191], v[220:223], v[22:25]
	v_mfma_f32_16x16x32_bf16 v[6:9], v[172:175], v[234:237], v[6:9]
	v_mfma_f32_16x16x32_bf16 v[2:5], v[188:191], v[234:237], v[2:5]
	s_setprio 0
	s_barrier
	s_add_i32 s52, 0, 0x18000
	v_add_u32_e32 v0, s52, v149
	s_add_i32 s53, 0, 0x1c000
	ds_read_b128 v[134:137], v0
	ds_read_b128 v[138:141], v0 offset:1024
	ds_read_b128 v[160:163], v0 offset:2048
	ds_read_b128 v[164:167], v0 offset:3072
	v_add_u32_e32 v0, s53, v149
	ds_read_b128 v[168:171], v0
	ds_read_b128 v[172:175], v0 offset:1024
	ds_read_b128 v[176:179], v0 offset:2048
	ds_read_b128 v[188:191], v0 offset:3072
	s_add_u32 s48, s48, 0x80000
	s_addc_u32 s49, s49, 0
	s_mov_b32 m0, s67
	ds_read_b128 v[192:195], v186 offset:32768
	ds_read_b128 v[204:207], v186 offset:33792
	ds_read_b128 v[208:211], v186 offset:34816
	ds_read_b128 v[212:215], v186 offset:35840
	ds_read_b128 v[216:219], v186 offset:36864
	ds_read_b128 v[220:223], v186 offset:37888
	ds_read_b128 v[224:227], v186 offset:38912
	ds_read_b128 v[234:237], v186 offset:39936
	global_load_lds_dwordx4 v14, s[48:49]
	s_mov_b32 m0, s68
	s_nop 0
	global_load_lds_dwordx4 v144, s[48:49]
	s_waitcnt vmcnt(8)
	s_waitcnt lgkmcnt(0)
	s_barrier
	s_setprio 1
	s_waitcnt lgkmcnt(0)
	v_mfma_f32_16x16x32_bf16 v[130:133], v[134:137], v[192:195], v[130:133]
	v_mfma_f32_16x16x32_bf16 v[126:129], v[160:163], v[192:195], v[126:129]
	v_mfma_f32_16x16x32_bf16 v[114:117], v[134:137], v[208:211], v[114:117]
	v_mfma_f32_16x16x32_bf16 v[110:113], v[160:163], v[208:211], v[110:113]
	v_mfma_f32_16x16x32_bf16 v[98:101], v[134:137], v[216:219], v[98:101]
	v_mfma_f32_16x16x32_bf16 v[94:97], v[160:163], v[216:219], v[94:97]
	v_mfma_f32_16x16x32_bf16 v[82:85], v[134:137], v[224:227], v[82:85]
	v_mfma_f32_16x16x32_bf16 v[78:81], v[160:163], v[224:227], v[78:81]
	v_mfma_f32_16x16x32_bf16 v[130:133], v[138:141], v[204:207], v[130:133]
	v_mfma_f32_16x16x32_bf16 v[126:129], v[164:167], v[204:207], v[126:129]
	v_mfma_f32_16x16x32_bf16 v[114:117], v[138:141], v[212:215], v[114:117]
	v_mfma_f32_16x16x32_bf16 v[110:113], v[164:167], v[212:215], v[110:113]
	v_mfma_f32_16x16x32_bf16 v[98:101], v[138:141], v[220:223], v[98:101]
	v_mfma_f32_16x16x32_bf16 v[94:97], v[164:167], v[220:223], v[94:97]
	v_mfma_f32_16x16x32_bf16 v[82:85], v[138:141], v[234:237], v[82:85]
	v_mfma_f32_16x16x32_bf16 v[78:81], v[164:167], v[234:237], v[78:81]
	s_setprio 0
	s_setprio 1
	v_mfma_f32_16x16x32_bf16 v[122:125], v[168:171], v[192:195], v[122:125]
	v_mfma_f32_16x16x32_bf16 v[118:121], v[176:179], v[192:195], v[118:121]
	v_mfma_f32_16x16x32_bf16 v[106:109], v[168:171], v[208:211], v[106:109]
	v_mfma_f32_16x16x32_bf16 v[102:105], v[176:179], v[208:211], v[102:105]
	v_mfma_f32_16x16x32_bf16 v[90:93], v[168:171], v[216:219], v[90:93]
	v_mfma_f32_16x16x32_bf16 v[86:89], v[176:179], v[216:219], v[86:89]
	v_mfma_f32_16x16x32_bf16 v[74:77], v[168:171], v[224:227], v[74:77]
	v_mfma_f32_16x16x32_bf16 v[70:73], v[176:179], v[224:227], v[70:73]
	v_mfma_f32_16x16x32_bf16 v[122:125], v[172:175], v[204:207], v[122:125]
	v_mfma_f32_16x16x32_bf16 v[118:121], v[188:191], v[204:207], v[118:121]
	v_mfma_f32_16x16x32_bf16 v[106:109], v[172:175], v[212:215], v[106:109]
	v_mfma_f32_16x16x32_bf16 v[102:105], v[188:191], v[212:215], v[102:105]
	v_mfma_f32_16x16x32_bf16 v[90:93], v[172:175], v[220:223], v[90:93]
	v_mfma_f32_16x16x32_bf16 v[86:89], v[188:191], v[220:223], v[86:89]
	v_mfma_f32_16x16x32_bf16 v[74:77], v[172:175], v[234:237], v[74:77]
	v_mfma_f32_16x16x32_bf16 v[70:73], v[188:191], v[234:237], v[70:73]
	s_setprio 0
	s_barrier
	s_add_i32 s48, s52, s56
	s_add_u32 s88, s46, s96
	s_addc_u32 s89, s47, s97
	s_mov_b32 m0, s48
	ds_read_b128 v[192:195], v186 offset:49152
	ds_read_b128 v[204:207], v186 offset:50176
	ds_read_b128 v[208:211], v186 offset:51200
	ds_read_b128 v[212:215], v186 offset:52224
	ds_read_b128 v[216:219], v186 offset:53248
	ds_read_b128 v[220:223], v186 offset:54272
	ds_read_b128 v[224:227], v186 offset:55296
	ds_read_b128 v[234:237], v186 offset:56320
	global_load_lds_dwordx4 v142, s[88:89]
	s_add_i32 m0, s48, 0x2000
	s_add_u32 s46, s46, 0x80080
	s_addc_u32 s47, s47, 0
	s_add_i32 s48, s53, s56
	global_load_lds_dwordx4 v146, s[88:89]
	s_mov_b32 m0, s48
	s_nop 0
	global_load_lds_dwordx4 v142, s[46:47]
	s_add_i32 m0, s48, 0x2000
	s_nop 0
	global_load_lds_dwordx4 v146, s[46:47]
	s_mov_b32 m0, s78
	s_nop 0
	global_load_lds_dwordx4 v14, s[98:99]
	s_mov_b32 m0, s79
	s_nop 0
	global_load_lds_dwordx4 v144, s[98:99]
	s_waitcnt vmcnt(8)
	s_waitcnt lgkmcnt(0)
	s_barrier
	s_setprio 1
	s_waitcnt lgkmcnt(0)
	v_mfma_f32_16x16x32_bf16 v[66:69], v[134:137], v[192:195], v[66:69]
	v_mfma_f32_16x16x32_bf16 v[62:65], v[160:163], v[192:195], v[62:65]
	v_mfma_f32_16x16x32_bf16 v[50:53], v[134:137], v[208:211], v[50:53]
	v_mfma_f32_16x16x32_bf16 v[46:49], v[160:163], v[208:211], v[46:49]
	v_mfma_f32_16x16x32_bf16 v[34:37], v[134:137], v[216:219], v[34:37]
	v_mfma_f32_16x16x32_bf16 v[30:33], v[160:163], v[216:219], v[30:33]
	v_mfma_f32_16x16x32_bf16 v[18:21], v[134:137], v[224:227], v[18:21]
	v_mfma_f32_16x16x32_bf16 v[10:13], v[160:163], v[224:227], v[10:13]
	v_mfma_f32_16x16x32_bf16 v[66:69], v[138:141], v[204:207], v[66:69]
	v_mfma_f32_16x16x32_bf16 v[62:65], v[164:167], v[204:207], v[62:65]
	v_mfma_f32_16x16x32_bf16 v[50:53], v[138:141], v[212:215], v[50:53]
	v_mfma_f32_16x16x32_bf16 v[46:49], v[164:167], v[212:215], v[46:49]
	v_mfma_f32_16x16x32_bf16 v[34:37], v[138:141], v[220:223], v[34:37]
	v_mfma_f32_16x16x32_bf16 v[30:33], v[164:167], v[220:223], v[30:33]
	v_mfma_f32_16x16x32_bf16 v[18:21], v[138:141], v[234:237], v[18:21]
	v_mfma_f32_16x16x32_bf16 v[10:13], v[164:167], v[234:237], v[10:13]
	s_setprio 0
	s_setprio 1
	v_mfma_f32_16x16x32_bf16 v[58:61], v[168:171], v[192:195], v[58:61]
	v_mfma_f32_16x16x32_bf16 v[54:57], v[176:179], v[192:195], v[54:57]
	v_mfma_f32_16x16x32_bf16 v[42:45], v[168:171], v[208:211], v[42:45]
	v_mfma_f32_16x16x32_bf16 v[38:41], v[176:179], v[208:211], v[38:41]
	v_mfma_f32_16x16x32_bf16 v[26:29], v[168:171], v[216:219], v[26:29]
	v_mfma_f32_16x16x32_bf16 v[22:25], v[176:179], v[216:219], v[22:25]
	v_mfma_f32_16x16x32_bf16 v[6:9], v[168:171], v[224:227], v[6:9]
	v_mfma_f32_16x16x32_bf16 v[2:5], v[176:179], v[224:227], v[2:5]
	v_mfma_f32_16x16x32_bf16 v[58:61], v[172:175], v[204:207], v[58:61]
	v_mfma_f32_16x16x32_bf16 v[54:57], v[188:191], v[204:207], v[54:57]
	v_mfma_f32_16x16x32_bf16 v[42:45], v[172:175], v[212:215], v[42:45]
	v_mfma_f32_16x16x32_bf16 v[38:41], v[188:191], v[212:215], v[38:41]
	v_mfma_f32_16x16x32_bf16 v[26:29], v[172:175], v[220:223], v[26:29]
	v_mfma_f32_16x16x32_bf16 v[22:25], v[188:191], v[220:223], v[22:25]
	v_mfma_f32_16x16x32_bf16 v[6:9], v[172:175], v[234:237], v[6:9]
	v_mfma_f32_16x16x32_bf16 v[2:5], v[188:191], v[234:237], v[2:5]
	s_setprio 0
	s_barrier
	s_add_i32 s41, s41, 2
	s_add_u32 s39, s39, 0x100
	s_addc_u32 s40, s40, 0
	s_add_u32 s6, s6, 0x100
	s_addc_u32 s7, s7, 0
	s_cmp_gt_u32 s41, 29
	s_cbranch_scc0 .LBB0_1045
	s_and_b64 vcc, exec, s[22:23]
	s_cbranch_vccz .LBB0_1048
	s_barrier

.LBB0_1321:
	s_add_u32 s36, s2, 0xfffc0080
	s_addc_u32 s37, s3, -1
	s_add_i32 s40, 0, 0x10000
	s_cmp_eq_u32 s34, 4
	s_cselect_b32 s39, s29, s37
	s_cselect_b32 s38, s28, s36
	v_add_u32_e32 v0, s40, v141
	s_cselect_b32 s37, s5, s27
	s_cselect_b32 s36, s7, s25
	s_add_i32 s58, 0, 0x14000
	ds_read_b128 v[148:151], v0
	ds_read_b128 v[152:155], v0 offset:1024
	ds_read_b128 v[156:159], v0 offset:2048
	ds_read_b128 v[160:163], v0 offset:3072
	v_add_u32_e32 v0, s58, v141
	ds_read_b128 v[164:167], v0
	ds_read_b128 v[168:171], v0 offset:1024
	ds_read_b128 v[172:175], v0 offset:2048
	ds_read_b128 v[176:179], v0 offset:3072
	s_add_i32 m0, s49, 0xc000
	ds_read_b128 v[180:183], v186
	ds_read_b128 v[188:191], v186 offset:1024
	ds_read_b128 v[192:195], v186 offset:2048
	ds_read_b128 v[204:207], v186 offset:3072
	ds_read_b128 v[208:211], v186 offset:4096
	ds_read_b128 v[212:215], v186 offset:5120
	ds_read_b128 v[216:219], v186 offset:6144
	ds_read_b128 v[220:223], v186 offset:7168
	global_load_lds_dwordx4 v146, s[2:3]
	s_add_i32 m0, s49, 0xe000
	s_nop 0
	global_load_lds_dwordx4 v144, s[2:3]
	s_waitcnt vmcnt(8)
	s_waitcnt lgkmcnt(0)
	s_barrier
	s_setprio 1
	s_waitcnt lgkmcnt(0)
	v_mfma_f32_16x16x32_bf16 v[130:133], v[148:151], v[180:183], v[130:133]
	v_mfma_f32_16x16x32_bf16 v[126:129], v[156:159], v[180:183], v[126:129]
	v_mfma_f32_16x16x32_bf16 v[114:117], v[148:151], v[192:195], v[114:117]
	v_mfma_f32_16x16x32_bf16 v[110:113], v[156:159], v[192:195], v[110:113]
	v_mfma_f32_16x16x32_bf16 v[98:101], v[148:151], v[208:211], v[98:101]
	v_mfma_f32_16x16x32_bf16 v[94:97], v[156:159], v[208:211], v[94:97]
	v_mfma_f32_16x16x32_bf16 v[82:85], v[148:151], v[216:219], v[82:85]
	v_mfma_f32_16x16x32_bf16 v[78:81], v[156:159], v[216:219], v[78:81]
	v_mfma_f32_16x16x32_bf16 v[130:133], v[152:155], v[188:191], v[130:133]
	v_mfma_f32_16x16x32_bf16 v[126:129], v[160:163], v[188:191], v[126:129]
	v_mfma_f32_16x16x32_bf16 v[114:117], v[152:155], v[204:207], v[114:117]
	v_mfma_f32_16x16x32_bf16 v[110:113], v[160:163], v[204:207], v[110:113]
	v_mfma_f32_16x16x32_bf16 v[98:101], v[152:155], v[212:215], v[98:101]
	v_mfma_f32_16x16x32_bf16 v[94:97], v[160:163], v[212:215], v[94:97]
	v_mfma_f32_16x16x32_bf16 v[82:85], v[152:155], v[220:223], v[82:85]
	v_mfma_f32_16x16x32_bf16 v[78:81], v[160:163], v[220:223], v[78:81]
	s_setprio 0
	s_setprio 1
	v_mfma_f32_16x16x32_bf16 v[122:125], v[164:167], v[180:183], v[122:125]
	v_mfma_f32_16x16x32_bf16 v[118:121], v[172:175], v[180:183], v[118:121]
	v_mfma_f32_16x16x32_bf16 v[106:109], v[164:167], v[192:195], v[106:109]
	v_mfma_f32_16x16x32_bf16 v[102:105], v[172:175], v[192:195], v[102:105]
	v_mfma_f32_16x16x32_bf16 v[90:93], v[164:167], v[208:211], v[90:93]
	v_mfma_f32_16x16x32_bf16 v[86:89], v[172:175], v[208:211], v[86:89]
	v_mfma_f32_16x16x32_bf16 v[74:77], v[164:167], v[216:219], v[74:77]
	v_mfma_f32_16x16x32_bf16 v[70:73], v[172:175], v[216:219], v[70:73]
	v_mfma_f32_16x16x32_bf16 v[122:125], v[168:171], v[188:191], v[122:125]
	v_mfma_f32_16x16x32_bf16 v[118:121], v[176:179], v[188:191], v[118:121]
	v_mfma_f32_16x16x32_bf16 v[106:109], v[168:171], v[204:207], v[106:109]
	v_mfma_f32_16x16x32_bf16 v[102:105], v[176:179], v[204:207], v[102:105]
	v_mfma_f32_16x16x32_bf16 v[90:93], v[168:171], v[212:215], v[90:93]
	v_mfma_f32_16x16x32_bf16 v[86:89], v[176:179], v[212:215], v[86:89]
	v_mfma_f32_16x16x32_bf16 v[74:77], v[168:171], v[220:223], v[74:77]
	v_mfma_f32_16x16x32_bf16 v[70:73], v[176:179], v[220:223], v[70:73]
	s_setprio 0
	s_barrier
	s_add_i32 s40, s40, s48
	s_mov_b32 m0, s40
	ds_read_b128 v[180:183], v186 offset:16384
	ds_read_b128 v[188:191], v186 offset:17408
	ds_read_b128 v[192:195], v186 offset:18432
	ds_read_b128 v[204:207], v186 offset:19456
	ds_read_b128 v[208:211], v186 offset:20480
	ds_read_b128 v[212:215], v186 offset:21504
	ds_read_b128 v[216:219], v186 offset:22528
	ds_read_b128 v[220:223], v186 offset:23552
	global_load_lds_dwordx4 v134, s[36:37]
	s_add_i32 m0, s40, 0x2000
	s_add_u32 s56, s36, 0x20000
	s_addc_u32 s57, s37, 0
	s_add_i32 s40, s58, s48
	global_load_lds_dwordx4 v138, s[36:37]
	s_mov_b32 m0, s40
	s_add_u32 s90, s38, s96
	s_addc_u32 s91, s39, s97
	global_load_lds_dwordx4 v134, s[56:57]
	s_add_i32 m0, s40, 0x2000
	s_nop 0
	global_load_lds_dwordx4 v138, s[56:57]
	s_mov_b32 m0, s49
	s_nop 0
	global_load_lds_dwordx4 v14, s[38:39]
	s_mov_b32 m0, s50
	s_nop 0
	global_load_lds_dwordx4 v136, s[38:39]
	s_waitcnt vmcnt(8)
	s_waitcnt lgkmcnt(0)
	s_barrier
	s_setprio 1
	s_waitcnt lgkmcnt(0)
	v_mfma_f32_16x16x32_bf16 v[66:69], v[148:151], v[180:183], v[66:69]
	v_mfma_f32_16x16x32_bf16 v[62:65], v[156:159], v[180:183], v[62:65]
	v_mfma_f32_16x16x32_bf16 v[50:53], v[148:151], v[192:195], v[50:53]
	v_mfma_f32_16x16x32_bf16 v[46:49], v[156:159], v[192:195], v[46:49]
	v_mfma_f32_16x16x32_bf16 v[34:37], v[148:151], v[208:211], v[34:37]
	v_mfma_f32_16x16x32_bf16 v[30:33], v[156:159], v[208:211], v[30:33]
	v_mfma_f32_16x16x32_bf16 v[18:21], v[148:151], v[216:219], v[18:21]
	v_mfma_f32_16x16x32_bf16 v[10:13], v[156:159], v[216:219], v[10:13]
	v_mfma_f32_16x16x32_bf16 v[66:69], v[152:155], v[188:191], v[66:69]
	v_mfma_f32_16x16x32_bf16 v[62:65], v[160:163], v[188:191], v[62:65]
	v_mfma_f32_16x16x32_bf16 v[50:53], v[152:155], v[204:207], v[50:53]
	v_mfma_f32_16x16x32_bf16 v[46:49], v[160:163], v[204:207], v[46:49]
	v_mfma_f32_16x16x32_bf16 v[34:37], v[152:155], v[212:215], v[34:37]
	v_mfma_f32_16x16x32_bf16 v[30:33], v[160:163], v[212:215], v[30:33]
	v_mfma_f32_16x16x32_bf16 v[18:21], v[152:155], v[220:223], v[18:21]
	v_mfma_f32_16x16x32_bf16 v[10:13], v[160:163], v[220:223], v[10:13]
	s_setprio 0
	s_setprio 1
	v_mfma_f32_16x16x32_bf16 v[58:61], v[164:167], v[180:183], v[58:61]
	v_mfma_f32_16x16x32_bf16 v[54:57], v[172:175], v[180:183], v[54:57]
	v_mfma_f32_16x16x32_bf16 v[42:45], v[164:167], v[192:195], v[42:45]
	v_mfma_f32_16x16x32_bf16 v[38:41], v[172:175], v[192:195], v[38:41]
	v_mfma_f32_16x16x32_bf16 v[26:29], v[164:167], v[208:211], v[26:29]
	v_mfma_f32_16x16x32_bf16 v[22:25], v[172:175], v[208:211], v[22:25]
	v_mfma_f32_16x16x32_bf16 v[6:9], v[164:167], v[216:219], v[6:9]
	v_mfma_f32_16x16x32_bf16 v[2:5], v[172:175], v[216:219], v[2:5]
	v_mfma_f32_16x16x32_bf16 v[58:61], v[168:171], v[188:191], v[58:61]
	v_mfma_f32_16x16x32_bf16 v[54:57], v[176:179], v[188:191], v[54:57]
	v_mfma_f32_16x16x32_bf16 v[42:45], v[168:171], v[204:207], v[42:45]
	v_mfma_f32_16x16x32_bf16 v[38:41], v[176:179], v[204:207], v[38:41]
	v_mfma_f32_16x16x32_bf16 v[26:29], v[168:171], v[212:215], v[26:29]
	v_mfma_f32_16x16x32_bf16 v[22:25], v[176:179], v[212:215], v[22:25]
	v_mfma_f32_16x16x32_bf16 v[6:9], v[168:171], v[220:223], v[6:9]
	v_mfma_f32_16x16x32_bf16 v[2:5], v[176:179], v[220:223], v[2:5]
	s_setprio 0
	s_barrier
	s_add_i32 s40, 0, 0x18000
	v_add_u32_e32 v0, s40, v141
	s_add_i32 s56, 0, 0x1c000
	ds_read_b128 v[148:151], v0
	ds_read_b128 v[152:155], v0 offset:1024
	ds_read_b128 v[156:159], v0 offset:2048
	ds_read_b128 v[160:163], v0 offset:3072
	v_add_u32_e32 v0, s56, v141
	ds_read_b128 v[164:167], v0
	ds_read_b128 v[168:171], v0 offset:1024
	ds_read_b128 v[172:175], v0 offset:2048
	ds_read_b128 v[176:179], v0 offset:3072
	s_add_u32 s38, s38, 0x40000
	s_addc_u32 s39, s39, 0
	s_mov_b32 m0, s51
	ds_read_b128 v[180:183], v186 offset:32768
	ds_read_b128 v[188:191], v186 offset:33792
	ds_read_b128 v[192:195], v186 offset:34816
	ds_read_b128 v[204:207], v186 offset:35840
	ds_read_b128 v[208:211], v186 offset:36864
	ds_read_b128 v[212:215], v186 offset:37888
	ds_read_b128 v[216:219], v186 offset:38912
	ds_read_b128 v[220:223], v186 offset:39936
	global_load_lds_dwordx4 v14, s[38:39]
	s_mov_b32 m0, s52
	s_nop 0
	global_load_lds_dwordx4 v136, s[38:39]
	s_waitcnt vmcnt(8)
	s_waitcnt lgkmcnt(0)
	s_barrier
	s_setprio 1
	s_waitcnt lgkmcnt(0)
	v_mfma_f32_16x16x32_bf16 v[130:133], v[148:151], v[180:183], v[130:133]
	v_mfma_f32_16x16x32_bf16 v[126:129], v[156:159], v[180:183], v[126:129]
	v_mfma_f32_16x16x32_bf16 v[114:117], v[148:151], v[192:195], v[114:117]
	v_mfma_f32_16x16x32_bf16 v[110:113], v[156:159], v[192:195], v[110:113]
	v_mfma_f32_16x16x32_bf16 v[98:101], v[148:151], v[208:211], v[98:101]
	v_mfma_f32_16x16x32_bf16 v[94:97], v[156:159], v[208:211], v[94:97]
	v_mfma_f32_16x16x32_bf16 v[82:85], v[148:151], v[216:219], v[82:85]
	v_mfma_f32_16x16x32_bf16 v[78:81], v[156:159], v[216:219], v[78:81]
	v_mfma_f32_16x16x32_bf16 v[130:133], v[152:155], v[188:191], v[130:133]
	v_mfma_f32_16x16x32_bf16 v[126:129], v[160:163], v[188:191], v[126:129]
	v_mfma_f32_16x16x32_bf16 v[114:117], v[152:155], v[204:207], v[114:117]
	v_mfma_f32_16x16x32_bf16 v[110:113], v[160:163], v[204:207], v[110:113]
	v_mfma_f32_16x16x32_bf16 v[98:101], v[152:155], v[212:215], v[98:101]
	v_mfma_f32_16x16x32_bf16 v[94:97], v[160:163], v[212:215], v[94:97]
	v_mfma_f32_16x16x32_bf16 v[82:85], v[152:155], v[220:223], v[82:85]
	v_mfma_f32_16x16x32_bf16 v[78:81], v[160:163], v[220:223], v[78:81]
	s_setprio 0
	s_setprio 1
	v_mfma_f32_16x16x32_bf16 v[122:125], v[164:167], v[180:183], v[122:125]
	v_mfma_f32_16x16x32_bf16 v[118:121], v[172:175], v[180:183], v[118:121]
	v_mfma_f32_16x16x32_bf16 v[106:109], v[164:167], v[192:195], v[106:109]
	v_mfma_f32_16x16x32_bf16 v[102:105], v[172:175], v[192:195], v[102:105]
	v_mfma_f32_16x16x32_bf16 v[90:93], v[164:167], v[208:211], v[90:93]
	v_mfma_f32_16x16x32_bf16 v[86:89], v[172:175], v[208:211], v[86:89]
	v_mfma_f32_16x16x32_bf16 v[74:77], v[164:167], v[216:219], v[74:77]
	v_mfma_f32_16x16x32_bf16 v[70:73], v[172:175], v[216:219], v[70:73]
	v_mfma_f32_16x16x32_bf16 v[122:125], v[168:171], v[188:191], v[122:125]
	v_mfma_f32_16x16x32_bf16 v[118:121], v[176:179], v[188:191], v[118:121]
	v_mfma_f32_16x16x32_bf16 v[106:109], v[168:171], v[204:207], v[106:109]
	v_mfma_f32_16x16x32_bf16 v[102:105], v[176:179], v[204:207], v[102:105]
	v_mfma_f32_16x16x32_bf16 v[90:93], v[168:171], v[212:215], v[90:93]
	v_mfma_f32_16x16x32_bf16 v[86:89], v[176:179], v[212:215], v[86:89]
	v_mfma_f32_16x16x32_bf16 v[74:77], v[168:171], v[220:223], v[74:77]
	v_mfma_f32_16x16x32_bf16 v[70:73], v[176:179], v[220:223], v[70:73]
	s_setprio 0
	s_barrier
	s_add_i32 s38, s40, s48
	s_add_u32 s88, s36, s96
	s_addc_u32 s89, s37, s97
	s_mov_b32 m0, s38
	ds_read_b128 v[180:183], v186 offset:49152
	ds_read_b128 v[188:191], v186 offset:50176
	ds_read_b128 v[192:195], v186 offset:51200
	ds_read_b128 v[204:207], v186 offset:52224
	ds_read_b128 v[208:211], v186 offset:53248
	ds_read_b128 v[212:215], v186 offset:54272
	ds_read_b128 v[216:219], v186 offset:55296
	ds_read_b128 v[220:223], v186 offset:56320
	global_load_lds_dwordx4 v134, s[88:89]
	s_add_i32 m0, s38, 0x2000
	s_add_u32 s36, s36, 0x20080
	s_addc_u32 s37, s37, 0
	s_add_i32 s38, s56, s48
	global_load_lds_dwordx4 v138, s[88:89]
	s_mov_b32 m0, s38
	s_nop 0
	global_load_lds_dwordx4 v134, s[36:37]
	s_add_i32 m0, s38, 0x2000
	s_nop 0
	global_load_lds_dwordx4 v138, s[36:37]
	s_mov_b32 m0, s53
	s_nop 0
	global_load_lds_dwordx4 v14, s[90:91]
	s_mov_b32 m0, s54
	s_nop 0
	global_load_lds_dwordx4 v136, s[90:91]
	s_waitcnt vmcnt(8)
	s_waitcnt lgkmcnt(0)
	s_barrier
	s_setprio 1
	s_waitcnt lgkmcnt(0)
	v_mfma_f32_16x16x32_bf16 v[66:69], v[148:151], v[180:183], v[66:69]
	v_mfma_f32_16x16x32_bf16 v[62:65], v[156:159], v[180:183], v[62:65]
	v_mfma_f32_16x16x32_bf16 v[50:53], v[148:151], v[192:195], v[50:53]
	v_mfma_f32_16x16x32_bf16 v[46:49], v[156:159], v[192:195], v[46:49]
	v_mfma_f32_16x16x32_bf16 v[34:37], v[148:151], v[208:211], v[34:37]
	v_mfma_f32_16x16x32_bf16 v[30:33], v[156:159], v[208:211], v[30:33]
	v_mfma_f32_16x16x32_bf16 v[18:21], v[148:151], v[216:219], v[18:21]
	v_mfma_f32_16x16x32_bf16 v[10:13], v[156:159], v[216:219], v[10:13]
	v_mfma_f32_16x16x32_bf16 v[66:69], v[152:155], v[188:191], v[66:69]
	v_mfma_f32_16x16x32_bf16 v[62:65], v[160:163], v[188:191], v[62:65]
	v_mfma_f32_16x16x32_bf16 v[50:53], v[152:155], v[204:207], v[50:53]
	v_mfma_f32_16x16x32_bf16 v[46:49], v[160:163], v[204:207], v[46:49]
	v_mfma_f32_16x16x32_bf16 v[34:37], v[152:155], v[212:215], v[34:37]
	v_mfma_f32_16x16x32_bf16 v[30:33], v[160:163], v[212:215], v[30:33]
	v_mfma_f32_16x16x32_bf16 v[18:21], v[152:155], v[220:223], v[18:21]
	v_mfma_f32_16x16x32_bf16 v[10:13], v[160:163], v[220:223], v[10:13]
	s_setprio 0
	s_setprio 1
	v_mfma_f32_16x16x32_bf16 v[58:61], v[164:167], v[180:183], v[58:61]
	v_mfma_f32_16x16x32_bf16 v[54:57], v[172:175], v[180:183], v[54:57]
	v_mfma_f32_16x16x32_bf16 v[42:45], v[164:167], v[192:195], v[42:45]
	v_mfma_f32_16x16x32_bf16 v[38:41], v[172:175], v[192:195], v[38:41]
	v_mfma_f32_16x16x32_bf16 v[26:29], v[164:167], v[208:211], v[26:29]
	v_mfma_f32_16x16x32_bf16 v[22:25], v[172:175], v[208:211], v[22:25]
	v_mfma_f32_16x16x32_bf16 v[6:9], v[164:167], v[216:219], v[6:9]
	v_mfma_f32_16x16x32_bf16 v[2:5], v[172:175], v[216:219], v[2:5]
	v_mfma_f32_16x16x32_bf16 v[58:61], v[168:171], v[188:191], v[58:61]
	v_mfma_f32_16x16x32_bf16 v[54:57], v[176:179], v[188:191], v[54:57]
	v_mfma_f32_16x16x32_bf16 v[42:45], v[168:171], v[204:207], v[42:45]
	v_mfma_f32_16x16x32_bf16 v[38:41], v[176:179], v[204:207], v[38:41]
	v_mfma_f32_16x16x32_bf16 v[26:29], v[168:171], v[212:215], v[26:29]
	v_mfma_f32_16x16x32_bf16 v[22:25], v[176:179], v[212:215], v[22:25]
	v_mfma_f32_16x16x32_bf16 v[6:9], v[168:171], v[220:223], v[6:9]
	v_mfma_f32_16x16x32_bf16 v[2:5], v[176:179], v[220:223], v[2:5]
	s_setprio 0
	s_barrier
	s_add_i32 s34, s34, 2
	s_add_u32 s25, s25, 0x100
	s_addc_u32 s27, s27, 0
	s_add_u32 s2, s2, 0x100
	s_addc_u32 s3, s3, 0
	s_cmp_gt_u32 s34, 5
	s_cbranch_scc0 .LBB0_1321
	s_and_b64 vcc, exec, s[22:23]
	s_cbranch_vccz .LBB0_1324
	s_barrier

.LBB0_2399:
	s_add_u32 s90, s22, s40
	s_addc_u32 s91, s23, s41
	s_add_u32 s90, s90, 0x80080
	s_addc_u32 s91, s91, 0
	s_add_u32 s44, s22, s40
	s_addc_u32 s45, s23, s41
	s_add_u32 s44, s44, 0x100
	s_addc_u32 s45, s45, 0
	s_add_u32 s67, s63, s40
	s_addc_u32 s68, s64, s41
	s_add_i32 s69, 0, 0x10000
	s_cmpk_eq_i32 s40, 0xf00
	s_cselect_b32 s47, s25, s45
	s_cselect_b32 s46, s34, s44
	s_cselect_b32 s45, s27, s68
	s_cselect_b32 s44, s65, s67
	s_add_i32 s67, 0, 0x14000
	v_add_u32_e32 v154, s69, v180
	v_add_u32_e32 v170, s67, v180
	ds_read_b128 v[142:145], v154
	ds_read_b128 v[146:149], v154 offset:1024
	ds_read_b128 v[150:153], v154 offset:2048
	ds_read_b128 v[154:157], v154 offset:3072
	ds_read_b128 v[158:161], v170
	ds_read_b128 v[162:165], v170 offset:1024
	ds_read_b128 v[166:169], v170 offset:2048
	ds_read_b128 v[170:173], v170 offset:3072
	s_add_i32 m0, s5, 0xc000
	ds_read_b128 v[174:177], v184
	ds_read_b128 v[186:189], v184 offset:1024
	ds_read_b128 v[190:193], v184 offset:2048
	ds_read_b128 v[194:197], v184 offset:3072
	ds_read_b128 v[200:203], v184 offset:4096
	ds_read_b128 v[204:207], v184 offset:5120
	ds_read_b128 v[208:211], v184 offset:6144
	ds_read_b128 v[212:215], v184 offset:7168
	global_load_lds_dwordx4 v136, s[90:91]
	s_add_i32 m0, s5, 0xe000
	s_nop 0
	global_load_lds_dwordx4 v134, s[90:91]
	s_waitcnt vmcnt(8)
	s_waitcnt lgkmcnt(0)
	s_barrier
	s_setprio 1
	s_waitcnt lgkmcnt(0)
	v_mfma_f32_16x16x32_bf16 v[130:133], v[142:145], v[174:177], v[130:133]
	v_mfma_f32_16x16x32_bf16 v[126:129], v[150:153], v[174:177], v[126:129]
	v_mfma_f32_16x16x32_bf16 v[122:125], v[142:145], v[190:193], v[122:125]
	v_mfma_f32_16x16x32_bf16 v[118:121], v[150:153], v[190:193], v[118:121]
	v_mfma_f32_16x16x32_bf16 v[114:117], v[142:145], v[200:203], v[114:117]
	v_mfma_f32_16x16x32_bf16 v[110:113], v[150:153], v[200:203], v[110:113]
	v_mfma_f32_16x16x32_bf16 v[106:109], v[142:145], v[208:211], v[106:109]
	v_mfma_f32_16x16x32_bf16 v[102:105], v[150:153], v[208:211], v[102:105]
	v_mfma_f32_16x16x32_bf16 v[130:133], v[146:149], v[186:189], v[130:133]
	v_mfma_f32_16x16x32_bf16 v[126:129], v[154:157], v[186:189], v[126:129]
	v_mfma_f32_16x16x32_bf16 v[122:125], v[146:149], v[194:197], v[122:125]
	v_mfma_f32_16x16x32_bf16 v[118:121], v[154:157], v[194:197], v[118:121]
	v_mfma_f32_16x16x32_bf16 v[114:117], v[146:149], v[204:207], v[114:117]
	v_mfma_f32_16x16x32_bf16 v[110:113], v[154:157], v[204:207], v[110:113]
	v_mfma_f32_16x16x32_bf16 v[106:109], v[146:149], v[212:215], v[106:109]
	v_mfma_f32_16x16x32_bf16 v[102:105], v[154:157], v[212:215], v[102:105]
	s_setprio 0
	s_setprio 1
	v_mfma_f32_16x16x32_bf16 v[98:101], v[158:161], v[174:177], v[98:101]
	v_mfma_f32_16x16x32_bf16 v[94:97], v[166:169], v[174:177], v[94:97]
	v_mfma_f32_16x16x32_bf16 v[90:93], v[158:161], v[190:193], v[90:93]
	v_mfma_f32_16x16x32_bf16 v[86:89], v[166:169], v[190:193], v[86:89]
	v_mfma_f32_16x16x32_bf16 v[82:85], v[158:161], v[200:203], v[82:85]
	v_mfma_f32_16x16x32_bf16 v[78:81], v[166:169], v[200:203], v[78:81]
	v_mfma_f32_16x16x32_bf16 v[74:77], v[158:161], v[208:211], v[74:77]
	v_mfma_f32_16x16x32_bf16 v[70:73], v[166:169], v[208:211], v[70:73]
	v_mfma_f32_16x16x32_bf16 v[98:101], v[162:165], v[186:189], v[98:101]
	v_mfma_f32_16x16x32_bf16 v[94:97], v[170:173], v[186:189], v[94:97]
	v_mfma_f32_16x16x32_bf16 v[90:93], v[162:165], v[194:197], v[90:93]
	v_mfma_f32_16x16x32_bf16 v[86:89], v[170:173], v[194:197], v[86:89]
	v_mfma_f32_16x16x32_bf16 v[82:85], v[162:165], v[204:207], v[82:85]
	v_mfma_f32_16x16x32_bf16 v[78:81], v[170:173], v[204:207], v[78:81]
	v_mfma_f32_16x16x32_bf16 v[74:77], v[162:165], v[212:215], v[74:77]
	v_mfma_f32_16x16x32_bf16 v[70:73], v[170:173], v[212:215], v[70:73]
	s_setprio 0
	s_barrier
	s_add_i32 s68, s69, s53
	s_mov_b32 m0, s68
	ds_read_b128 v[174:177], v184 offset:16384
	ds_read_b128 v[186:189], v184 offset:17408
	ds_read_b128 v[190:193], v184 offset:18432
	ds_read_b128 v[194:197], v184 offset:19456
	ds_read_b128 v[200:203], v184 offset:20480
	ds_read_b128 v[204:207], v184 offset:21504
	ds_read_b128 v[208:211], v184 offset:22528
	ds_read_b128 v[212:215], v184 offset:23552
	global_load_lds_dwordx4 v0, s[44:45]
	s_add_i32 m0, s68, 0x2000
	s_add_u32 s68, s44, 0x80000
	s_addc_u32 s69, s45, 0
	s_add_i32 s67, s67, s53
	global_load_lds_dwordx4 v14, s[44:45]
	s_mov_b32 m0, s67
	s_add_u32 s92, s46, s96
	s_addc_u32 s93, s47, s97
	global_load_lds_dwordx4 v0, s[68:69]
	s_add_i32 m0, s67, 0x2000
	s_nop 0
	global_load_lds_dwordx4 v14, s[68:69]
	s_mov_b32 m0, s5
	s_nop 0
	global_load_lds_dwordx4 v0, s[46:47]
	s_mov_b32 m0, s7
	s_nop 0
	global_load_lds_dwordx4 v14, s[46:47]
	s_waitcnt vmcnt(8)
	s_waitcnt lgkmcnt(0)
	s_barrier
	s_setprio 1
	s_waitcnt lgkmcnt(0)
	v_mfma_f32_16x16x32_bf16 v[66:69], v[142:145], v[174:177], v[66:69]
	v_mfma_f32_16x16x32_bf16 v[62:65], v[150:153], v[174:177], v[62:65]
	v_mfma_f32_16x16x32_bf16 v[58:61], v[142:145], v[190:193], v[58:61]
	v_mfma_f32_16x16x32_bf16 v[54:57], v[150:153], v[190:193], v[54:57]
	v_mfma_f32_16x16x32_bf16 v[50:53], v[142:145], v[200:203], v[50:53]
	v_mfma_f32_16x16x32_bf16 v[46:49], v[150:153], v[200:203], v[46:49]
	v_mfma_f32_16x16x32_bf16 v[42:45], v[142:145], v[208:211], v[42:45]
	v_mfma_f32_16x16x32_bf16 v[38:41], v[150:153], v[208:211], v[38:41]
	v_mfma_f32_16x16x32_bf16 v[66:69], v[146:149], v[186:189], v[66:69]
	v_mfma_f32_16x16x32_bf16 v[62:65], v[154:157], v[186:189], v[62:65]
	v_mfma_f32_16x16x32_bf16 v[58:61], v[146:149], v[194:197], v[58:61]
	v_mfma_f32_16x16x32_bf16 v[54:57], v[154:157], v[194:197], v[54:57]
	v_mfma_f32_16x16x32_bf16 v[50:53], v[146:149], v[204:207], v[50:53]
	v_mfma_f32_16x16x32_bf16 v[46:49], v[154:157], v[204:207], v[46:49]
	v_mfma_f32_16x16x32_bf16 v[42:45], v[146:149], v[212:215], v[42:45]
	v_mfma_f32_16x16x32_bf16 v[38:41], v[154:157], v[212:215], v[38:41]
	s_setprio 0
	s_setprio 1
	v_mfma_f32_16x16x32_bf16 v[34:37], v[158:161], v[174:177], v[34:37]
	v_mfma_f32_16x16x32_bf16 v[30:33], v[166:169], v[174:177], v[30:33]
	v_mfma_f32_16x16x32_bf16 v[26:29], v[158:161], v[190:193], v[26:29]
	v_mfma_f32_16x16x32_bf16 v[22:25], v[166:169], v[190:193], v[22:25]
	v_mfma_f32_16x16x32_bf16 v[18:21], v[158:161], v[200:203], v[18:21]
	v_mfma_f32_16x16x32_bf16 v[10:13], v[166:169], v[200:203], v[10:13]
	v_mfma_f32_16x16x32_bf16 v[6:9], v[158:161], v[208:211], v[6:9]
	v_mfma_f32_16x16x32_bf16 v[2:5], v[166:169], v[208:211], v[2:5]
	v_mfma_f32_16x16x32_bf16 v[34:37], v[162:165], v[186:189], v[34:37]
	v_mfma_f32_16x16x32_bf16 v[30:33], v[170:173], v[186:189], v[30:33]
	v_mfma_f32_16x16x32_bf16 v[26:29], v[162:165], v[194:197], v[26:29]
	v_mfma_f32_16x16x32_bf16 v[22:25], v[170:173], v[194:197], v[22:25]
	v_mfma_f32_16x16x32_bf16 v[18:21], v[162:165], v[204:207], v[18:21]
	v_mfma_f32_16x16x32_bf16 v[10:13], v[170:173], v[204:207], v[10:13]
	v_mfma_f32_16x16x32_bf16 v[6:9], v[162:165], v[212:215], v[6:9]
	v_mfma_f32_16x16x32_bf16 v[2:5], v[170:173], v[212:215], v[2:5]
	s_setprio 0
	s_barrier
	s_add_i32 s67, 0, 0x18000
	s_add_i32 s68, 0, 0x1c000
	v_add_u32_e32 v154, s67, v180
	v_add_u32_e32 v170, s68, v180
	ds_read_b128 v[142:145], v154
	ds_read_b128 v[146:149], v154 offset:1024
	ds_read_b128 v[150:153], v154 offset:2048
	ds_read_b128 v[154:157], v154 offset:3072
	ds_read_b128 v[158:161], v170
	ds_read_b128 v[162:165], v170 offset:1024
	ds_read_b128 v[166:169], v170 offset:2048
	ds_read_b128 v[170:173], v170 offset:3072
	s_add_u32 s46, s46, 0x80000
	s_addc_u32 s47, s47, 0
	s_mov_b32 m0, s54
	ds_read_b128 v[174:177], v184 offset:32768
	ds_read_b128 v[186:189], v184 offset:33792
	ds_read_b128 v[190:193], v184 offset:34816
	ds_read_b128 v[194:197], v184 offset:35840
	ds_read_b128 v[200:203], v184 offset:36864
	ds_read_b128 v[204:207], v184 offset:37888
	ds_read_b128 v[208:211], v184 offset:38912
	ds_read_b128 v[212:215], v184 offset:39936
	global_load_lds_dwordx4 v0, s[46:47]
	s_mov_b32 m0, s55
	s_nop 0
	global_load_lds_dwordx4 v14, s[46:47]
	s_waitcnt vmcnt(8)
	s_waitcnt lgkmcnt(0)
	s_barrier
	s_setprio 1
	s_waitcnt lgkmcnt(0)
	v_mfma_f32_16x16x32_bf16 v[130:133], v[142:145], v[174:177], v[130:133]
	v_mfma_f32_16x16x32_bf16 v[126:129], v[150:153], v[174:177], v[126:129]
	v_mfma_f32_16x16x32_bf16 v[122:125], v[142:145], v[190:193], v[122:125]
	v_mfma_f32_16x16x32_bf16 v[118:121], v[150:153], v[190:193], v[118:121]
	v_mfma_f32_16x16x32_bf16 v[114:117], v[142:145], v[200:203], v[114:117]
	v_mfma_f32_16x16x32_bf16 v[110:113], v[150:153], v[200:203], v[110:113]
	v_mfma_f32_16x16x32_bf16 v[106:109], v[142:145], v[208:211], v[106:109]
	v_mfma_f32_16x16x32_bf16 v[102:105], v[150:153], v[208:211], v[102:105]
	v_mfma_f32_16x16x32_bf16 v[130:133], v[146:149], v[186:189], v[130:133]
	v_mfma_f32_16x16x32_bf16 v[126:129], v[154:157], v[186:189], v[126:129]
	v_mfma_f32_16x16x32_bf16 v[122:125], v[146:149], v[194:197], v[122:125]
	v_mfma_f32_16x16x32_bf16 v[118:121], v[154:157], v[194:197], v[118:121]
	v_mfma_f32_16x16x32_bf16 v[114:117], v[146:149], v[204:207], v[114:117]
	v_mfma_f32_16x16x32_bf16 v[110:113], v[154:157], v[204:207], v[110:113]
	v_mfma_f32_16x16x32_bf16 v[106:109], v[146:149], v[212:215], v[106:109]
	v_mfma_f32_16x16x32_bf16 v[102:105], v[154:157], v[212:215], v[102:105]
	s_setprio 0
	s_setprio 1
	v_mfma_f32_16x16x32_bf16 v[98:101], v[158:161], v[174:177], v[98:101]
	v_mfma_f32_16x16x32_bf16 v[94:97], v[166:169], v[174:177], v[94:97]
	v_mfma_f32_16x16x32_bf16 v[90:93], v[158:161], v[190:193], v[90:93]
	v_mfma_f32_16x16x32_bf16 v[86:89], v[166:169], v[190:193], v[86:89]
	v_mfma_f32_16x16x32_bf16 v[82:85], v[158:161], v[200:203], v[82:85]
	v_mfma_f32_16x16x32_bf16 v[78:81], v[166:169], v[200:203], v[78:81]
	v_mfma_f32_16x16x32_bf16 v[74:77], v[158:161], v[208:211], v[74:77]
	v_mfma_f32_16x16x32_bf16 v[70:73], v[166:169], v[208:211], v[70:73]
	v_mfma_f32_16x16x32_bf16 v[98:101], v[162:165], v[186:189], v[98:101]
	v_mfma_f32_16x16x32_bf16 v[94:97], v[170:173], v[186:189], v[94:97]
	v_mfma_f32_16x16x32_bf16 v[90:93], v[162:165], v[194:197], v[90:93]
	v_mfma_f32_16x16x32_bf16 v[86:89], v[170:173], v[194:197], v[86:89]
	v_mfma_f32_16x16x32_bf16 v[82:85], v[162:165], v[204:207], v[82:85]
	v_mfma_f32_16x16x32_bf16 v[78:81], v[170:173], v[204:207], v[78:81]
	v_mfma_f32_16x16x32_bf16 v[74:77], v[162:165], v[212:215], v[74:77]
	v_mfma_f32_16x16x32_bf16 v[70:73], v[170:173], v[212:215], v[70:73]
	s_setprio 0
	s_barrier
	s_add_i32 s46, s67, s53
	s_add_u32 s90, s44, s96
	s_addc_u32 s91, s45, s97
	s_mov_b32 m0, s46
	ds_read_b128 v[174:177], v184 offset:49152
	ds_read_b128 v[186:189], v184 offset:50176
	ds_read_b128 v[190:193], v184 offset:51200
	ds_read_b128 v[194:197], v184 offset:52224
	ds_read_b128 v[200:203], v184 offset:53248
	ds_read_b128 v[204:207], v184 offset:54272
	ds_read_b128 v[208:211], v184 offset:55296
	ds_read_b128 v[212:215], v184 offset:56320
	global_load_lds_dwordx4 v0, s[90:91]
	s_add_i32 m0, s46, 0x2000
	s_add_u32 s44, s44, 0x80080
	s_addc_u32 s45, s45, 0
	s_add_i32 s46, s68, s53
	global_load_lds_dwordx4 v14, s[90:91]
	s_mov_b32 m0, s46
	s_nop 0
	global_load_lds_dwordx4 v0, s[44:45]
	s_add_i32 m0, s46, 0x2000
	s_nop 0
	global_load_lds_dwordx4 v14, s[44:45]
	s_mov_b32 m0, s59
	s_nop 0
	global_load_lds_dwordx4 v0, s[92:93]
	s_mov_b32 m0, s60
	s_nop 0
	global_load_lds_dwordx4 v14, s[92:93]
	s_waitcnt vmcnt(8)
	s_waitcnt lgkmcnt(0)
	s_barrier
	s_setprio 1
	s_waitcnt lgkmcnt(0)
	v_mfma_f32_16x16x32_bf16 v[66:69], v[142:145], v[174:177], v[66:69]
	v_mfma_f32_16x16x32_bf16 v[62:65], v[150:153], v[174:177], v[62:65]
	v_mfma_f32_16x16x32_bf16 v[58:61], v[142:145], v[190:193], v[58:61]
	v_mfma_f32_16x16x32_bf16 v[54:57], v[150:153], v[190:193], v[54:57]
	v_mfma_f32_16x16x32_bf16 v[50:53], v[142:145], v[200:203], v[50:53]
	v_mfma_f32_16x16x32_bf16 v[46:49], v[150:153], v[200:203], v[46:49]
	v_mfma_f32_16x16x32_bf16 v[42:45], v[142:145], v[208:211], v[42:45]
	v_mfma_f32_16x16x32_bf16 v[38:41], v[150:153], v[208:211], v[38:41]
	v_mfma_f32_16x16x32_bf16 v[66:69], v[146:149], v[186:189], v[66:69]
	v_mfma_f32_16x16x32_bf16 v[62:65], v[154:157], v[186:189], v[62:65]
	v_mfma_f32_16x16x32_bf16 v[58:61], v[146:149], v[194:197], v[58:61]
	v_mfma_f32_16x16x32_bf16 v[54:57], v[154:157], v[194:197], v[54:57]
	v_mfma_f32_16x16x32_bf16 v[50:53], v[146:149], v[204:207], v[50:53]
	v_mfma_f32_16x16x32_bf16 v[46:49], v[154:157], v[204:207], v[46:49]
	v_mfma_f32_16x16x32_bf16 v[42:45], v[146:149], v[212:215], v[42:45]
	v_mfma_f32_16x16x32_bf16 v[38:41], v[154:157], v[212:215], v[38:41]
	s_setprio 0
	s_setprio 1
	v_mfma_f32_16x16x32_bf16 v[34:37], v[158:161], v[174:177], v[34:37]
	v_mfma_f32_16x16x32_bf16 v[30:33], v[166:169], v[174:177], v[30:33]
	v_mfma_f32_16x16x32_bf16 v[26:29], v[158:161], v[190:193], v[26:29]
	v_mfma_f32_16x16x32_bf16 v[22:25], v[166:169], v[190:193], v[22:25]
	v_mfma_f32_16x16x32_bf16 v[18:21], v[158:161], v[200:203], v[18:21]
	v_mfma_f32_16x16x32_bf16 v[10:13], v[166:169], v[200:203], v[10:13]
	v_mfma_f32_16x16x32_bf16 v[6:9], v[158:161], v[208:211], v[6:9]
	v_mfma_f32_16x16x32_bf16 v[2:5], v[166:169], v[208:211], v[2:5]
	v_mfma_f32_16x16x32_bf16 v[34:37], v[162:165], v[186:189], v[34:37]
	v_mfma_f32_16x16x32_bf16 v[30:33], v[170:173], v[186:189], v[30:33]
	v_mfma_f32_16x16x32_bf16 v[26:29], v[162:165], v[194:197], v[26:29]
	v_mfma_f32_16x16x32_bf16 v[22:25], v[170:173], v[194:197], v[22:25]
	v_mfma_f32_16x16x32_bf16 v[18:21], v[162:165], v[204:207], v[18:21]
	v_mfma_f32_16x16x32_bf16 v[10:13], v[170:173], v[204:207], v[10:13]
	v_mfma_f32_16x16x32_bf16 v[6:9], v[162:165], v[212:215], v[6:9]
	v_mfma_f32_16x16x32_bf16 v[2:5], v[170:173], v[212:215], v[2:5]
	s_setprio 0
	s_barrier
	s_add_i32 s66, s66, 2
	s_add_u32 s40, s40, 0x100
	s_addc_u32 s41, s41, 0
	s_cmp_gt_u32 s66, 29
	s_cbranch_scc0 .LBB0_2399
	s_and_b64 vcc, exec, s[18:19]
	s_cbranch_vccz .LBB0_2402
	s_barrier
